# v16 + first K-loop iteration of every GEMM unit peeled; in it the first two DMA waits are skipped except for the phase's first unit (they only retired loads already retired by the previous unit's epil
# speedup vs baseline: 1.0049x; 1.0041x over previous
.LBB0_211:
	s_mov_b32 s32, 0
	v_writelane_b32 v254, s80, 24
	s_nop 1
	v_writelane_b32 v254, s81, 25
	v_writelane_b32 v254, s82, 26
	v_writelane_b32 v254, s83, 27
	s_add_u32 s81, s62, 0x1f200000
	s_addc_u32 s85, s63, 0
	s_add_u32 s0, s62, 0x2f200000
	s_addc_u32 s1, s63, 0
	s_add_u32 s56, s62, 0x39200000
	s_addc_u32 s57, s63, 0
	s_add_u32 s82, s62, 0x45200000
	s_addc_u32 s83, s63, 0
	s_add_u32 s48, s62, 0x27200000
	s_addc_u32 s49, s63, 0
	s_add_u32 s50, s62, 0x2b200000
	s_addc_u32 s51, s63, 0
	s_waitcnt lgkmcnt(0)
	s_add_u32 s70, s62, 0x33200000
	v_writelane_b32 v254, s0, 28
	s_addc_u32 s71, s63, 0
	s_nop 0
	v_writelane_b32 v254, s1, 29
	s_add_u32 s0, s62, 0x3f200000
	v_writelane_b32 v254, s0, 30
	s_addc_u32 s0, s63, 0
	s_add_u32 s54, s62, 0x4d200000
	s_addc_u32 s55, s63, 0
	s_cmp_lt_i32 s88, 3
	v_writelane_b32 v254, s0, 31
	s_cselect_b64 s[0:1], -1, 0
	s_cmp_gt_i32 s89, 2
	s_cselect_b64 s[2:3], -1, 0
	s_and_b64 s[0:1], s[0:1], s[2:3]
	s_andn2_b64 vcc, exec, s[0:1]
	s_cbranch_vccnz .LBB0_371
	s_cmpk_lt_i32 s33, 0x1700
	s_cselect_b64 s[0:1], -1, 0
	s_cmpk_gt_i32 s33, 0x16ff
	v_readfirstlane_b32 s2, v0
	s_cbranch_scc0 .LBB0_215
	s_andn2_b64 vcc, exec, s[0:1]
	s_cbranch_vccz .LBB0_216

.LBB0_223:
	s_ashr_i32 s23, s22, 31
	s_lshl_b64 s[24:25], s[22:23], 20
	s_add_u32 s24, s81, s24
	s_addc_u32 s25, s85, s25
	s_and_b64 s[26:27], s[2:3], exec
	s_cselect_b32 s5, s25, s29
	s_cselect_b32 s7, s24, s28
	s_ashr_i32 s21, s20, 31
	s_lshl_b64 s[26:27], s[20:21], 20
	s_add_u32 s26, s92, s26
	s_addc_u32 s27, s97, s27
	s_and_b64 s[34:35], s[2:3], exec
	s_cselect_b32 s21, s27, s31
	s_cselect_b32 s23, s26, s30
	s_add_u32 s28, s28, 0x80080
	s_addc_u32 s29, s29, 0
	s_add_u32 s36, s30, 0x100
	v_mov_b32_e32 v2, 0
	s_addc_u32 s37, s31, 0
	s_mov_b32 s38, -2
	v_mov_b32_e32 v3, v2
	v_mov_b32_e32 v4, v2
	v_mov_b32_e32 v5, v2
	v_mov_b32_e32 v6, v2
	v_mov_b32_e32 v7, v2
	v_mov_b32_e32 v8, v2
	v_mov_b32_e32 v9, v2
	v_mov_b32_e32 v18, v2
	v_mov_b32_e32 v19, v2
	v_mov_b32_e32 v20, v2
	v_mov_b32_e32 v21, v2
	v_mov_b32_e32 v22, v2
	v_mov_b32_e32 v23, v2
	v_mov_b32_e32 v24, v2
	v_mov_b32_e32 v25, v2
	v_mov_b32_e32 v34, v2
	v_mov_b32_e32 v35, v2
	v_mov_b32_e32 v36, v2
	v_mov_b32_e32 v37, v2
	v_mov_b32_e32 v38, v2
	v_mov_b32_e32 v39, v2
	v_mov_b32_e32 v40, v2
	v_mov_b32_e32 v41, v2
	v_mov_b32_e32 v58, v2
	v_mov_b32_e32 v59, v2
	v_mov_b32_e32 v60, v2
	v_mov_b32_e32 v61, v2
	v_mov_b32_e32 v62, v2
	v_mov_b32_e32 v63, v2
	v_mov_b32_e32 v64, v2
	v_mov_b32_e32 v65, v2
	v_mov_b32_e32 v10, v2
	v_mov_b32_e32 v11, v2
	v_mov_b32_e32 v12, v2
	v_mov_b32_e32 v13, v2
	v_mov_b32_e32 v14, v2
	v_mov_b32_e32 v15, v2
	v_mov_b32_e32 v16, v2
	v_mov_b32_e32 v17, v2
	v_mov_b32_e32 v26, v2
	v_mov_b32_e32 v27, v2
	v_mov_b32_e32 v28, v2
	v_mov_b32_e32 v29, v2
	v_mov_b32_e32 v30, v2
	v_mov_b32_e32 v31, v2
	v_mov_b32_e32 v32, v2
	v_mov_b32_e32 v33, v2
	v_mov_b32_e32 v42, v2
	v_mov_b32_e32 v43, v2
	v_mov_b32_e32 v44, v2
	v_mov_b32_e32 v45, v2
	v_mov_b32_e32 v54, v2
	v_mov_b32_e32 v55, v2
	v_mov_b32_e32 v56, v2
	v_mov_b32_e32 v57, v2
	v_mov_b32_e32 v74, v2
	v_mov_b32_e32 v75, v2
	v_mov_b32_e32 v76, v2
	v_mov_b32_e32 v77, v2
	v_mov_b32_e32 v78, v2
	v_mov_b32_e32 v79, v2
	v_mov_b32_e32 v80, v2
	v_mov_b32_e32 v81, v2
	v_mov_b32_e32 v82, v2
	v_mov_b32_e32 v83, v2
	v_mov_b32_e32 v84, v2
	v_mov_b32_e32 v85, v2
	v_mov_b32_e32 v86, v2
	v_mov_b32_e32 v87, v2
	v_mov_b32_e32 v88, v2
	v_mov_b32_e32 v89, v2
	v_mov_b32_e32 v90, v2
	v_mov_b32_e32 v91, v2
	v_mov_b32_e32 v92, v2
	v_mov_b32_e32 v93, v2
	v_mov_b32_e32 v94, v2
	v_mov_b32_e32 v95, v2
	v_mov_b32_e32 v96, v2
	v_mov_b32_e32 v97, v2
	v_mov_b32_e32 v106, v2
	v_mov_b32_e32 v107, v2
	v_mov_b32_e32 v108, v2
	v_mov_b32_e32 v109, v2
	v_mov_b32_e32 v110, v2
	v_mov_b32_e32 v111, v2
	v_mov_b32_e32 v112, v2
	v_mov_b32_e32 v113, v2
	v_mov_b32_e32 v122, v2
	v_mov_b32_e32 v123, v2
	v_mov_b32_e32 v124, v2
	v_mov_b32_e32 v125, v2
	v_mov_b32_e32 v126, v2
	v_mov_b32_e32 v127, v2
	v_mov_b32_e32 v128, v2
	v_mov_b32_e32 v129, v2
	v_mov_b32_e32 v98, v2
	v_mov_b32_e32 v99, v2
	v_mov_b32_e32 v100, v2
	v_mov_b32_e32 v101, v2
	v_mov_b32_e32 v102, v2
	v_mov_b32_e32 v103, v2
	v_mov_b32_e32 v104, v2
	v_mov_b32_e32 v105, v2
	v_mov_b32_e32 v114, v2
	v_mov_b32_e32 v115, v2
	v_mov_b32_e32 v116, v2
	v_mov_b32_e32 v117, v2
	v_mov_b32_e32 v118, v2
	v_mov_b32_e32 v119, v2
	v_mov_b32_e32 v120, v2
	v_mov_b32_e32 v121, v2
	v_mov_b32_e32 v130, v2
	v_mov_b32_e32 v131, v2
	v_mov_b32_e32 v132, v2
	v_mov_b32_e32 v133, v2
	v_mov_b32_e32 v134, v2
	v_mov_b32_e32 v135, v2
	v_mov_b32_e32 v136, v2
	v_mov_b32_e32 v137, v2
	v_mov_b32_e32 v138, v2
	v_mov_b32_e32 v139, v2
	v_mov_b32_e32 v140, v2
	v_mov_b32_e32 v141, v2
	v_mov_b32_e32 v142, v2
	v_mov_b32_e32 v143, v2
	v_mov_b32_e32 v144, v2
	v_mov_b32_e32 v145, v2
	ds_read_b128 v[46:49], v196
	ds_read_b128 v[50:53], v196 offset:1024
	ds_read_b128 v[66:69], v196 offset:2048
	ds_read_b128 v[70:73], v196 offset:3072
	ds_read_b128 v[164:167], v197
	ds_read_b128 v[168:171], v197 offset:1024
	ds_read_b128 v[172:175], v197 offset:2048
	ds_read_b128 v[176:179], v197 offset:3072
	s_add_u32 s30, s28, 0xfff80080
	s_addc_u32 s31, s29, -1
	s_cmp_eq_u32 s38, 28
	s_cselect_b32 s35, s5, s31
	s_cselect_b32 s34, s7, s30
	s_cselect_b32 s31, s21, s37
	s_cselect_b32 s30, s23, s36
	s_add_i32 m0, s17, 0xc000
	ds_read_b128 v[184:187], v198
	ds_read_b128 v[188:191], v198 offset:1024
	ds_read_b128 v[200:203], v198 offset:2048
	ds_read_b128 v[204:207], v198 offset:3072
	ds_read_b128 v[208:211], v198 offset:4096
	ds_read_b128 v[212:215], v198 offset:5120
	ds_read_b128 v[216:219], v198 offset:6144
	ds_read_b128 v[220:223], v198 offset:7168
	global_load_lds_dwordx4 v156, s[28:29]
	s_add_i32 m0, s17, 0xe000
	s_nop 0
	global_load_lds_dwordx4 v158, s[28:29]
	s_cmp_lg_u32 s32, 0
	s_cbranch_scc1 .Lpw0a
	s_waitcnt vmcnt(8)
.Lpw0a:
	s_waitcnt lgkmcnt(0)
	s_barrier
	s_setprio 1
	s_waitcnt lgkmcnt(0)
	v_mfma_i32_16x16x64_i8 v[142:145], v[46:49], v[184:187], v[142:145]
	v_mfma_i32_16x16x64_i8 v[138:141], v[66:69], v[184:187], v[138:141]
	v_mfma_i32_16x16x64_i8 v[134:137], v[46:49], v[200:203], v[134:137]
	v_mfma_i32_16x16x64_i8 v[130:133], v[66:69], v[200:203], v[130:133]
	v_mfma_i32_16x16x64_i8 v[118:121], v[46:49], v[208:211], v[118:121]
	v_mfma_i32_16x16x64_i8 v[114:117], v[66:69], v[208:211], v[114:117]
	v_mfma_i32_16x16x64_i8 v[102:105], v[46:49], v[216:219], v[102:105]
	v_mfma_i32_16x16x64_i8 v[98:101], v[66:69], v[216:219], v[98:101]
	v_mfma_i32_16x16x64_i8 v[142:145], v[50:53], v[188:191], v[142:145]
	v_mfma_i32_16x16x64_i8 v[138:141], v[70:73], v[188:191], v[138:141]
	v_mfma_i32_16x16x64_i8 v[134:137], v[50:53], v[204:207], v[134:137]
	v_mfma_i32_16x16x64_i8 v[130:133], v[70:73], v[204:207], v[130:133]
	v_mfma_i32_16x16x64_i8 v[118:121], v[50:53], v[212:215], v[118:121]
	v_mfma_i32_16x16x64_i8 v[114:117], v[70:73], v[212:215], v[114:117]
	v_mfma_i32_16x16x64_i8 v[102:105], v[50:53], v[220:223], v[102:105]
	v_mfma_i32_16x16x64_i8 v[98:101], v[70:73], v[220:223], v[98:101]
	s_setprio 0
	s_setprio 1
	v_mfma_i32_16x16x64_i8 v[126:129], v[164:167], v[184:187], v[126:129]
	v_mfma_i32_16x16x64_i8 v[122:125], v[172:175], v[184:187], v[122:125]
	v_mfma_i32_16x16x64_i8 v[110:113], v[164:167], v[200:203], v[110:113]
	v_mfma_i32_16x16x64_i8 v[106:109], v[172:175], v[200:203], v[106:109]
	v_mfma_i32_16x16x64_i8 v[94:97], v[164:167], v[208:211], v[94:97]
	v_mfma_i32_16x16x64_i8 v[90:93], v[172:175], v[208:211], v[90:93]
	v_mfma_i32_16x16x64_i8 v[86:89], v[164:167], v[216:219], v[86:89]
	v_mfma_i32_16x16x64_i8 v[82:85], v[172:175], v[216:219], v[82:85]
	v_mfma_i32_16x16x64_i8 v[126:129], v[168:171], v[188:191], v[126:129]
	v_mfma_i32_16x16x64_i8 v[122:125], v[176:179], v[188:191], v[122:125]
	v_mfma_i32_16x16x64_i8 v[110:113], v[168:171], v[204:207], v[110:113]
	v_mfma_i32_16x16x64_i8 v[106:109], v[176:179], v[204:207], v[106:109]
	v_mfma_i32_16x16x64_i8 v[94:97], v[168:171], v[212:215], v[94:97]
	v_mfma_i32_16x16x64_i8 v[90:93], v[176:179], v[212:215], v[90:93]
	v_mfma_i32_16x16x64_i8 v[86:89], v[168:171], v[220:223], v[86:89]
	v_mfma_i32_16x16x64_i8 v[82:85], v[176:179], v[220:223], v[82:85]
	s_setprio 0
	s_barrier
	s_add_i32 s39, s76, s9
	s_mov_b32 m0, s39
	ds_read_b128 v[184:187], v198 offset:16384
	ds_read_b128 v[188:191], v198 offset:17408
	ds_read_b128 v[200:203], v198 offset:18432
	ds_read_b128 v[204:207], v198 offset:19456
	ds_read_b128 v[208:211], v198 offset:20480
	ds_read_b128 v[212:215], v198 offset:21504
	ds_read_b128 v[216:219], v198 offset:22528
	ds_read_b128 v[220:223], v198 offset:23552
	global_load_lds_dwordx4 v146, s[30:31]
	s_add_i32 m0, s39, 0x2000
	s_add_u32 s46, s30, 0x80000
	s_addc_u32 s47, s31, 0
	s_add_i32 s39, s77, s9
	global_load_lds_dwordx4 v148, s[30:31]
	s_mov_b32 m0, s39
	s_nop 0
	global_load_lds_dwordx4 v146, s[46:47]
	s_add_i32 m0, s39, 0x2000
	s_nop 0
	global_load_lds_dwordx4 v148, s[46:47]
	s_mov_b32 m0, s17
	s_nop 0
	global_load_lds_dwordx4 v146, s[34:35]
	s_mov_b32 m0, s40
	s_nop 0
	global_load_lds_dwordx4 v148, s[34:35]
	s_cmp_lg_u32 s32, 0
	s_cbranch_scc1 .Lpw0b
	s_waitcnt vmcnt(8)
.Lpw0b:
	s_mov_b32 s32, 1
	s_waitcnt lgkmcnt(0)
	s_barrier
	s_setprio 1
	s_waitcnt lgkmcnt(0)
	v_mfma_i32_16x16x64_i8 v[78:81], v[46:49], v[184:187], v[78:81]
	v_mfma_i32_16x16x64_i8 v[74:77], v[66:69], v[184:187], v[74:77]
	v_mfma_i32_16x16x64_i8 v[54:57], v[46:49], v[200:203], v[54:57]
	v_mfma_i32_16x16x64_i8 v[42:45], v[66:69], v[200:203], v[42:45]
	v_mfma_i32_16x16x64_i8 v[30:33], v[46:49], v[208:211], v[30:33]
	v_mfma_i32_16x16x64_i8 v[26:29], v[66:69], v[208:211], v[26:29]
	v_mfma_i32_16x16x64_i8 v[14:17], v[46:49], v[216:219], v[14:17]
	v_mfma_i32_16x16x64_i8 v[10:13], v[66:69], v[216:219], v[10:13]
	v_mfma_i32_16x16x64_i8 v[78:81], v[50:53], v[188:191], v[78:81]
	v_mfma_i32_16x16x64_i8 v[74:77], v[70:73], v[188:191], v[74:77]
	v_mfma_i32_16x16x64_i8 v[54:57], v[50:53], v[204:207], v[54:57]
	v_mfma_i32_16x16x64_i8 v[42:45], v[70:73], v[204:207], v[42:45]
	v_mfma_i32_16x16x64_i8 v[30:33], v[50:53], v[212:215], v[30:33]
	v_mfma_i32_16x16x64_i8 v[26:29], v[70:73], v[212:215], v[26:29]
	v_mfma_i32_16x16x64_i8 v[14:17], v[50:53], v[220:223], v[14:17]
	v_mfma_i32_16x16x64_i8 v[10:13], v[70:73], v[220:223], v[10:13]
	s_setprio 0
	s_setprio 1
	v_mfma_i32_16x16x64_i8 v[38:41], v[164:167], v[200:203], v[38:41]
	v_mfma_i32_16x16x64_i8 v[34:37], v[172:175], v[200:203], v[34:37]
	v_mfma_i32_16x16x64_i8 v[22:25], v[164:167], v[208:211], v[22:25]
	v_mfma_i32_16x16x64_i8 v[18:21], v[172:175], v[208:211], v[18:21]
	v_mfma_i32_16x16x64_i8 v[6:9], v[164:167], v[216:219], v[6:9]
	v_mfma_i32_16x16x64_i8 v[2:5], v[172:175], v[216:219], v[2:5]
	v_mfma_i32_16x16x64_i8 v[46:49], v[164:167], v[184:187], v[62:65]
	v_mfma_i32_16x16x64_i8 v[50:53], v[172:175], v[184:187], v[58:61]
	v_mfma_i32_16x16x64_i8 v[38:41], v[168:171], v[204:207], v[38:41]
	v_mfma_i32_16x16x64_i8 v[34:37], v[176:179], v[204:207], v[34:37]
	v_mfma_i32_16x16x64_i8 v[22:25], v[168:171], v[212:215], v[22:25]
	v_mfma_i32_16x16x64_i8 v[18:21], v[176:179], v[212:215], v[18:21]
	v_mfma_i32_16x16x64_i8 v[6:9], v[168:171], v[220:223], v[6:9]
	v_mfma_i32_16x16x64_i8 v[2:5], v[176:179], v[220:223], v[2:5]
	v_mfma_i32_16x16x64_i8 v[46:49], v[168:171], v[188:191], v[46:49]
	v_mfma_i32_16x16x64_i8 v[50:53], v[176:179], v[188:191], v[50:53]
	s_setprio 0
	s_barrier
	s_add_i32 s39, 0, 0x18000
	v_add_u32_e32 v1, s39, v194
	s_add_i32 s46, 0, 0x1c000
	ds_read_b128 v[58:61], v1
	ds_read_b128 v[62:65], v1 offset:1024
	ds_read_b128 v[66:69], v1 offset:2048
	ds_read_b128 v[70:73], v1 offset:3072
	v_add_u32_e32 v1, s46, v194
	ds_read_b128 v[164:167], v1
	ds_read_b128 v[168:171], v1 offset:1024
	ds_read_b128 v[172:175], v1 offset:2048
	ds_read_b128 v[176:179], v1 offset:3072
	s_add_u32 s34, s34, 0x80000
	s_addc_u32 s35, s35, 0
	s_mov_b32 m0, s41
	ds_read_b128 v[184:187], v198 offset:32768
	ds_read_b128 v[188:191], v198 offset:33792
	ds_read_b128 v[200:203], v198 offset:34816
	ds_read_b128 v[204:207], v198 offset:35840
	ds_read_b128 v[208:211], v198 offset:36864
	ds_read_b128 v[212:215], v198 offset:37888
	ds_read_b128 v[216:219], v198 offset:38912
	ds_read_b128 v[220:223], v198 offset:39936
	global_load_lds_dwordx4 v146, s[34:35]
	s_mov_b32 m0, s42
	s_nop 0
	global_load_lds_dwordx4 v148, s[34:35]
	s_waitcnt vmcnt(8)
	s_waitcnt lgkmcnt(0)
	s_barrier
	s_setprio 1
	s_waitcnt lgkmcnt(0)
	v_mfma_i32_16x16x64_i8 v[142:145], v[58:61], v[184:187], v[142:145]
	v_mfma_i32_16x16x64_i8 v[138:141], v[66:69], v[184:187], v[138:141]
	v_mfma_i32_16x16x64_i8 v[134:137], v[58:61], v[200:203], v[134:137]
	v_mfma_i32_16x16x64_i8 v[130:133], v[66:69], v[200:203], v[130:133]
	v_mfma_i32_16x16x64_i8 v[118:121], v[58:61], v[208:211], v[118:121]
	v_mfma_i32_16x16x64_i8 v[114:117], v[66:69], v[208:211], v[114:117]
	v_mfma_i32_16x16x64_i8 v[102:105], v[58:61], v[216:219], v[102:105]
	v_mfma_i32_16x16x64_i8 v[98:101], v[66:69], v[216:219], v[98:101]
	v_mfma_i32_16x16x64_i8 v[142:145], v[62:65], v[188:191], v[142:145]
	v_mfma_i32_16x16x64_i8 v[138:141], v[70:73], v[188:191], v[138:141]
	v_mfma_i32_16x16x64_i8 v[134:137], v[62:65], v[204:207], v[134:137]
	v_mfma_i32_16x16x64_i8 v[130:133], v[70:73], v[204:207], v[130:133]
	v_mfma_i32_16x16x64_i8 v[118:121], v[62:65], v[212:215], v[118:121]
	v_mfma_i32_16x16x64_i8 v[114:117], v[70:73], v[212:215], v[114:117]
	v_mfma_i32_16x16x64_i8 v[102:105], v[62:65], v[220:223], v[102:105]
	v_mfma_i32_16x16x64_i8 v[98:101], v[70:73], v[220:223], v[98:101]
	s_setprio 0
	s_setprio 1
	v_mfma_i32_16x16x64_i8 v[126:129], v[164:167], v[184:187], v[126:129]
	v_mfma_i32_16x16x64_i8 v[122:125], v[172:175], v[184:187], v[122:125]
	v_mfma_i32_16x16x64_i8 v[110:113], v[164:167], v[200:203], v[110:113]
	v_mfma_i32_16x16x64_i8 v[106:109], v[172:175], v[200:203], v[106:109]
	v_mfma_i32_16x16x64_i8 v[94:97], v[164:167], v[208:211], v[94:97]
	v_mfma_i32_16x16x64_i8 v[90:93], v[172:175], v[208:211], v[90:93]
	v_mfma_i32_16x16x64_i8 v[86:89], v[164:167], v[216:219], v[86:89]
	v_mfma_i32_16x16x64_i8 v[82:85], v[172:175], v[216:219], v[82:85]
	v_mfma_i32_16x16x64_i8 v[126:129], v[168:171], v[188:191], v[126:129]
	v_mfma_i32_16x16x64_i8 v[122:125], v[176:179], v[188:191], v[122:125]
	v_mfma_i32_16x16x64_i8 v[110:113], v[168:171], v[204:207], v[110:113]
	v_mfma_i32_16x16x64_i8 v[106:109], v[176:179], v[204:207], v[106:109]
	v_mfma_i32_16x16x64_i8 v[94:97], v[168:171], v[212:215], v[94:97]
	v_mfma_i32_16x16x64_i8 v[90:93], v[176:179], v[212:215], v[90:93]
	v_mfma_i32_16x16x64_i8 v[86:89], v[168:171], v[220:223], v[86:89]
	v_mfma_i32_16x16x64_i8 v[82:85], v[176:179], v[220:223], v[82:85]
	s_setprio 0
	s_barrier
	s_add_u32 s98, s34, 0xfff80080
	s_addc_u32 s99, s35, -1
	s_add_i32 s34, s39, s9
	s_mov_b32 m0, s34
	ds_read_b128 v[184:187], v198 offset:49152
	ds_read_b128 v[188:191], v198 offset:50176
	ds_read_b128 v[200:203], v198 offset:51200
	ds_read_b128 v[204:207], v198 offset:52224
	ds_read_b128 v[208:211], v198 offset:53248
	ds_read_b128 v[212:215], v198 offset:54272
	ds_read_b128 v[216:219], v198 offset:55296
	ds_read_b128 v[220:223], v198 offset:56320
	s_add_u32 s100, s30, 0x80
	s_addc_u32 s101, s31, 0
	global_load_lds_dwordx4 v146, s[100:101]
	s_add_i32 m0, s34, 0x2000
	s_add_u32 s30, s30, 0x80080
	s_addc_u32 s31, s31, 0
	s_add_i32 s34, s46, s9
	global_load_lds_dwordx4 v148, s[100:101]
	s_mov_b32 m0, s34
	s_nop 0
	global_load_lds_dwordx4 v146, s[30:31]
	s_add_i32 m0, s34, 0x2000
	s_nop 0
	global_load_lds_dwordx4 v148, s[30:31]
	s_mov_b32 m0, s72
	s_nop 0
	global_load_lds_dwordx4 v146, s[98:99]
	s_mov_b32 m0, s73
	s_nop 0
	global_load_lds_dwordx4 v148, s[98:99]
	s_waitcnt vmcnt(8)
	s_waitcnt lgkmcnt(0)
	s_barrier
	s_setprio 1
	s_waitcnt lgkmcnt(0)
	v_mfma_i32_16x16x64_i8 v[78:81], v[58:61], v[184:187], v[78:81]
	v_mfma_i32_16x16x64_i8 v[74:77], v[66:69], v[184:187], v[74:77]
	v_mfma_i32_16x16x64_i8 v[54:57], v[58:61], v[200:203], v[54:57]
	v_mfma_i32_16x16x64_i8 v[42:45], v[66:69], v[200:203], v[42:45]
	v_mfma_i32_16x16x64_i8 v[30:33], v[58:61], v[208:211], v[30:33]
	v_mfma_i32_16x16x64_i8 v[26:29], v[66:69], v[208:211], v[26:29]
	v_mfma_i32_16x16x64_i8 v[14:17], v[58:61], v[216:219], v[14:17]
	v_mfma_i32_16x16x64_i8 v[10:13], v[66:69], v[216:219], v[10:13]
	v_mfma_i32_16x16x64_i8 v[78:81], v[62:65], v[188:191], v[78:81]
	v_mfma_i32_16x16x64_i8 v[74:77], v[70:73], v[188:191], v[74:77]
	v_mfma_i32_16x16x64_i8 v[54:57], v[62:65], v[204:207], v[54:57]
	v_mfma_i32_16x16x64_i8 v[42:45], v[70:73], v[204:207], v[42:45]
	v_mfma_i32_16x16x64_i8 v[30:33], v[62:65], v[212:215], v[30:33]
	v_mfma_i32_16x16x64_i8 v[26:29], v[70:73], v[212:215], v[26:29]
	v_mfma_i32_16x16x64_i8 v[14:17], v[62:65], v[220:223], v[14:17]
	v_mfma_i32_16x16x64_i8 v[10:13], v[70:73], v[220:223], v[10:13]
	s_setprio 0
	s_setprio 1
	v_mfma_i32_16x16x64_i8 v[46:49], v[164:167], v[184:187], v[46:49]
	v_mfma_i32_16x16x64_i8 v[62:65], v[168:171], v[188:191], v[46:49]
	v_mfma_i32_16x16x64_i8 v[46:49], v[172:175], v[184:187], v[50:53]
	v_mfma_i32_16x16x64_i8 v[38:41], v[164:167], v[200:203], v[38:41]
	v_mfma_i32_16x16x64_i8 v[34:37], v[172:175], v[200:203], v[34:37]
	v_mfma_i32_16x16x64_i8 v[22:25], v[164:167], v[208:211], v[22:25]
	v_mfma_i32_16x16x64_i8 v[18:21], v[172:175], v[208:211], v[18:21]
	v_mfma_i32_16x16x64_i8 v[6:9], v[164:167], v[216:219], v[6:9]
	v_mfma_i32_16x16x64_i8 v[2:5], v[172:175], v[216:219], v[2:5]
	v_mfma_i32_16x16x64_i8 v[58:61], v[176:179], v[188:191], v[46:49]
	v_mfma_i32_16x16x64_i8 v[38:41], v[168:171], v[204:207], v[38:41]
	v_mfma_i32_16x16x64_i8 v[34:37], v[176:179], v[204:207], v[34:37]
	v_mfma_i32_16x16x64_i8 v[22:25], v[168:171], v[212:215], v[22:25]
	v_mfma_i32_16x16x64_i8 v[18:21], v[176:179], v[212:215], v[18:21]
	v_mfma_i32_16x16x64_i8 v[6:9], v[168:171], v[220:223], v[6:9]
	v_mfma_i32_16x16x64_i8 v[2:5], v[176:179], v[220:223], v[2:5]
	s_setprio 0
	s_barrier
	s_add_i32 s38, s38, 2
	s_add_u32 s28, s28, 0x100
	s_addc_u32 s29, s29, 0
	s_add_u32 s36, s36, 0x100
	s_addc_u32 s37, s37, 0
	s_cmp_gt_u32 s38, 29

.LBB0_532:
	s_mov_b32 s32, 0
	s_add_u32 s20, s62, 0x5b200000
	s_addc_u32 s21, s63, 0
	s_cmp_lt_i32 s88, 6
	s_cselect_b64 s[0:1], -1, 0
	s_cmp_gt_i32 s89, 5
	s_cselect_b64 s[2:3], -1, 0
	s_and_b64 s[0:1], s[0:1], s[2:3]
	s_andn2_b64 vcc, exec, s[0:1]
	s_cbranch_vccnz .LBB0_635
	v_lshlrev_b32_e32 v2, 4, v0
	v_and_b32_e32 v1, 32, v0
	v_or_b32_e32 v173, 0x2000, v2
	v_bfe_u32 v169, v0, 2, 4
	v_bitop3_b32 v1, v2, v1, 48 bitop3:0x6c
	v_lshrrev_b32_e32 v2, 7, v173
	s_movk_i32 s0, 0x70
	v_lshrrev_b32_e32 v3, 3, v0
	v_and_or_b32 v193, v2, s0, v169
	v_bfe_u32 v2, v0, 4, 2
	v_and_or_b32 v192, v3, 48, v169
	v_lshlrev_b32_e32 v179, 3, v2
	v_lshlrev_b32_e32 v146, 4, v2
	v_lshlrev_b32_e32 v2, 6, v0
	v_lshlrev_b32_e32 v3, 2, v0
	v_and_b32_e32 v165, 64, v0
	v_and_b32_e32 v2, 0x3c0, v2
	v_and_b32_e32 v3, 32, v3
	s_cmpk_lt_i32 s33, 0x400
	v_readfirstlane_b32 s10, v0
	v_or_b32_e32 v185, v1, v165
	v_and_b32_e32 v183, 15, v0
	s_cselect_b64 s[0:1], -1, 0
	s_cmpk_gt_i32 s33, 0x3ff
	v_bitop3_b32 v189, v146, v3, v2 bitop3:0x36
	s_cbranch_scc1 .LBB0_557
	s_ashr_i32 s40, s33, 31
	s_lshr_b32 s2, s40, 29
	s_add_i32 s4, s33, s2
	s_and_b32 s2, s4, -8
	s_sub_i32 s6, s33, s2
	s_cmp_gt_i32 s6, -1
	s_cbranch_scc0 .LBB0_536
	s_lshl_b32 s5, s6, 7
	s_cbranch_execz .LBB0_537
	s_branch .LBB0_538

.LBB0_549:
	s_ashr_i32 s25, s24, 31
	s_lshl_b64 s[26:27], s[24:25], 19
	s_add_u32 s26, s48, s26
	s_addc_u32 s27, s49, s27
	s_and_b64 s[28:29], s[2:3], exec
	s_cselect_b32 s25, s27, s35
	s_cselect_b32 s70, s26, s34
	s_ashr_i32 s23, s22, 31
	s_lshl_b64 s[28:29], s[22:23], 19
	v_readlane_b32 s72, v254, 10
	s_add_u32 s28, s72, s28
	s_addc_u32 s29, s79, s29
	s_and_b64 s[38:39], s[2:3], exec
	s_cselect_b32 s23, s29, s37
	s_cselect_b32 s71, s28, s36
	s_add_u32 s34, s34, 0x40080
	s_addc_u32 s35, s35, 0
	v_readlane_b32 s73, v254, 11
	v_readlane_b32 s74, v254, 12
	s_add_u32 s72, s36, 0x100
	v_mov_b32_e32 v2, 0
	s_addc_u32 s73, s37, 0
	s_mov_b32 s74, -2
	v_mov_b32_e32 v3, v2
	v_mov_b32_e32 v4, v2
	v_mov_b32_e32 v5, v2
	v_mov_b32_e32 v6, v2
	v_mov_b32_e32 v7, v2
	v_mov_b32_e32 v8, v2
	v_mov_b32_e32 v9, v2
	v_mov_b32_e32 v18, v2
	v_mov_b32_e32 v19, v2
	v_mov_b32_e32 v20, v2
	v_mov_b32_e32 v21, v2
	v_mov_b32_e32 v22, v2
	v_mov_b32_e32 v23, v2
	v_mov_b32_e32 v24, v2
	v_mov_b32_e32 v25, v2
	v_mov_b32_e32 v34, v2
	v_mov_b32_e32 v35, v2
	v_mov_b32_e32 v36, v2
	v_mov_b32_e32 v37, v2
	v_mov_b32_e32 v38, v2
	v_mov_b32_e32 v39, v2
	v_mov_b32_e32 v40, v2
	v_mov_b32_e32 v41, v2
	s_waitcnt vmcnt(0)
	v_mov_b32_e32 v50, v2
	v_mov_b32_e32 v51, v2
	v_mov_b32_e32 v52, v2
	v_mov_b32_e32 v53, v2
	v_mov_b32_e32 v54, v2
	v_mov_b32_e32 v55, v2
	v_mov_b32_e32 v56, v2
	v_mov_b32_e32 v57, v2
	v_mov_b32_e32 v10, v2
	v_mov_b32_e32 v11, v2
	v_mov_b32_e32 v12, v2
	v_mov_b32_e32 v13, v2
	v_mov_b32_e32 v14, v2
	v_mov_b32_e32 v15, v2
	v_mov_b32_e32 v16, v2
	v_mov_b32_e32 v17, v2
	v_mov_b32_e32 v26, v2
	v_mov_b32_e32 v27, v2
	v_mov_b32_e32 v28, v2
	v_mov_b32_e32 v29, v2
	v_mov_b32_e32 v30, v2
	v_mov_b32_e32 v31, v2
	v_mov_b32_e32 v32, v2
	v_mov_b32_e32 v33, v2
	v_mov_b32_e32 v42, v2
	v_mov_b32_e32 v43, v2
	v_mov_b32_e32 v44, v2
	v_mov_b32_e32 v45, v2
	v_mov_b32_e32 v46, v2
	v_mov_b32_e32 v47, v2
	v_mov_b32_e32 v48, v2
	v_mov_b32_e32 v49, v2
	v_mov_b32_e32 v58, v2
	v_mov_b32_e32 v59, v2
	v_mov_b32_e32 v60, v2
	v_mov_b32_e32 v61, v2
	v_mov_b32_e32 v62, v2
	v_mov_b32_e32 v63, v2
	v_mov_b32_e32 v64, v2
	v_mov_b32_e32 v65, v2
	v_mov_b32_e32 v66, v2
	v_mov_b32_e32 v67, v2
	v_mov_b32_e32 v68, v2
	v_mov_b32_e32 v69, v2
	v_mov_b32_e32 v70, v2
	v_mov_b32_e32 v71, v2
	v_mov_b32_e32 v72, v2
	v_mov_b32_e32 v73, v2
	v_mov_b32_e32 v82, v2
	v_mov_b32_e32 v83, v2
	v_mov_b32_e32 v84, v2
	v_mov_b32_e32 v85, v2
	v_mov_b32_e32 v86, v2
	v_mov_b32_e32 v87, v2
	v_mov_b32_e32 v88, v2
	v_mov_b32_e32 v89, v2
	v_mov_b32_e32 v98, v2
	v_mov_b32_e32 v99, v2
	v_mov_b32_e32 v100, v2
	v_mov_b32_e32 v101, v2
	v_mov_b32_e32 v102, v2
	v_mov_b32_e32 v103, v2
	v_mov_b32_e32 v104, v2
	v_mov_b32_e32 v105, v2
	v_mov_b32_e32 v130, v2
	v_mov_b32_e32 v131, v2
	v_mov_b32_e32 v132, v2
	v_mov_b32_e32 v133, v2
	v_mov_b32_e32 v134, v2
	v_mov_b32_e32 v135, v2
	v_mov_b32_e32 v136, v2
	v_mov_b32_e32 v137, v2
	v_mov_b32_e32 v74, v2
	v_mov_b32_e32 v75, v2
	v_mov_b32_e32 v76, v2
	v_mov_b32_e32 v77, v2
	v_mov_b32_e32 v78, v2
	v_mov_b32_e32 v79, v2
	v_mov_b32_e32 v80, v2
	v_mov_b32_e32 v81, v2
	v_mov_b32_e32 v90, v2
	v_mov_b32_e32 v91, v2
	v_mov_b32_e32 v92, v2
	v_mov_b32_e32 v93, v2
	v_mov_b32_e32 v94, v2
	v_mov_b32_e32 v95, v2
	v_mov_b32_e32 v96, v2
	v_mov_b32_e32 v97, v2
	v_mov_b32_e32 v122, v2
	v_mov_b32_e32 v123, v2
	v_mov_b32_e32 v124, v2
	v_mov_b32_e32 v125, v2
	v_mov_b32_e32 v126, v2
	v_mov_b32_e32 v127, v2
	v_mov_b32_e32 v128, v2
	v_mov_b32_e32 v129, v2
	v_mov_b32_e32 v138, v2
	v_mov_b32_e32 v139, v2
	v_mov_b32_e32 v140, v2
	v_mov_b32_e32 v141, v2
	v_mov_b32_e32 v142, v2
	v_mov_b32_e32 v143, v2
	v_mov_b32_e32 v144, v2
	v_mov_b32_e32 v145, v2
	v_readlane_b32 s75, v254, 13
	ds_read_b128 v[106:109], v147
	ds_read_b128 v[110:113], v147 offset:1024
	ds_read_b128 v[114:117], v147 offset:2048
	ds_read_b128 v[118:121], v147 offset:3072
	ds_read_b128 v[174:177], v197
	ds_read_b128 v[200:203], v197 offset:1024
	ds_read_b128 v[204:207], v197 offset:2048
	ds_read_b128 v[208:211], v197 offset:3072
	s_add_u32 s36, s34, 0xfffc0080
	s_addc_u32 s37, s35, -1
	s_cmp_eq_u32 s74, 12
	s_cselect_b32 s39, s25, s37
	s_cselect_b32 s38, s70, s36
	s_cselect_b32 s37, s23, s73
	s_cselect_b32 s36, s71, s72
	s_add_i32 m0, s31, 0xc000
	ds_read_b128 v[212:215], v198
	ds_read_b128 v[216:219], v198 offset:1024
	ds_read_b128 v[220:223], v198 offset:2048
	ds_read_b128 v[224:227], v198 offset:3072
	ds_read_b128 v[228:231], v198 offset:4096
	ds_read_b128 v[232:235], v198 offset:5120
	ds_read_b128 v[236:239], v198 offset:6144
	ds_read_b128 v[240:243], v198 offset:7168
	global_load_lds_dwordx4 v154, s[34:35]
	s_add_i32 m0, s31, 0xe000
	s_nop 0
	global_load_lds_dwordx4 v156, s[34:35]
	s_cmp_lg_u32 s32, 0
	s_cbranch_scc1 .Lpw1a
	s_waitcnt vmcnt(8)
.Lpw1a:
	s_waitcnt lgkmcnt(0)
	s_barrier
	s_setprio 1
	s_waitcnt lgkmcnt(0)
	v_mfma_i32_16x16x64_i8 v[142:145], v[106:109], v[212:215], v[142:145]
	v_mfma_i32_16x16x64_i8 v[138:141], v[114:117], v[212:215], v[138:141]
	v_mfma_i32_16x16x64_i8 v[126:129], v[106:109], v[220:223], v[126:129]
	v_mfma_i32_16x16x64_i8 v[122:125], v[114:117], v[220:223], v[122:125]
	v_mfma_i32_16x16x64_i8 v[94:97], v[106:109], v[228:231], v[94:97]
	v_mfma_i32_16x16x64_i8 v[90:93], v[114:117], v[228:231], v[90:93]
	v_mfma_i32_16x16x64_i8 v[78:81], v[106:109], v[236:239], v[78:81]
	v_mfma_i32_16x16x64_i8 v[74:77], v[114:117], v[236:239], v[74:77]
	v_mfma_i32_16x16x64_i8 v[142:145], v[110:113], v[216:219], v[142:145]
	v_mfma_i32_16x16x64_i8 v[138:141], v[118:121], v[216:219], v[138:141]
	v_mfma_i32_16x16x64_i8 v[126:129], v[110:113], v[224:227], v[126:129]
	v_mfma_i32_16x16x64_i8 v[122:125], v[118:121], v[224:227], v[122:125]
	v_mfma_i32_16x16x64_i8 v[94:97], v[110:113], v[232:235], v[94:97]
	v_mfma_i32_16x16x64_i8 v[90:93], v[118:121], v[232:235], v[90:93]
	v_mfma_i32_16x16x64_i8 v[78:81], v[110:113], v[240:243], v[78:81]
	v_mfma_i32_16x16x64_i8 v[74:77], v[118:121], v[240:243], v[74:77]
	s_setprio 0
	s_setprio 1
	v_mfma_i32_16x16x64_i8 v[134:137], v[174:177], v[212:215], v[134:137]
	v_mfma_i32_16x16x64_i8 v[130:133], v[204:207], v[212:215], v[130:133]
	v_mfma_i32_16x16x64_i8 v[102:105], v[174:177], v[220:223], v[102:105]
	v_mfma_i32_16x16x64_i8 v[98:101], v[204:207], v[220:223], v[98:101]
	v_mfma_i32_16x16x64_i8 v[86:89], v[174:177], v[228:231], v[86:89]
	v_mfma_i32_16x16x64_i8 v[82:85], v[204:207], v[228:231], v[82:85]
	v_mfma_i32_16x16x64_i8 v[70:73], v[174:177], v[236:239], v[70:73]
	v_mfma_i32_16x16x64_i8 v[66:69], v[204:207], v[236:239], v[66:69]
	v_mfma_i32_16x16x64_i8 v[134:137], v[200:203], v[216:219], v[134:137]
	v_mfma_i32_16x16x64_i8 v[130:133], v[208:211], v[216:219], v[130:133]
	v_mfma_i32_16x16x64_i8 v[102:105], v[200:203], v[224:227], v[102:105]
	v_mfma_i32_16x16x64_i8 v[98:101], v[208:211], v[224:227], v[98:101]
	v_mfma_i32_16x16x64_i8 v[86:89], v[200:203], v[232:235], v[86:89]
	v_mfma_i32_16x16x64_i8 v[82:85], v[208:211], v[232:235], v[82:85]
	v_mfma_i32_16x16x64_i8 v[70:73], v[200:203], v[240:243], v[70:73]
	v_mfma_i32_16x16x64_i8 v[66:69], v[208:211], v[240:243], v[66:69]
	s_setprio 0
	s_barrier
	s_add_i32 s75, s67, s41
	s_mov_b32 m0, s75
	ds_read_b128 v[212:215], v198 offset:16384
	ds_read_b128 v[216:219], v198 offset:17408
	ds_read_b128 v[220:223], v198 offset:18432
	ds_read_b128 v[224:227], v198 offset:19456
	ds_read_b128 v[228:231], v198 offset:20480
	ds_read_b128 v[232:235], v198 offset:21504
	ds_read_b128 v[236:239], v198 offset:22528
	ds_read_b128 v[240:243], v198 offset:23552
	global_load_lds_dwordx4 v148, s[36:37]
	s_add_i32 m0, s75, 0x2000
	s_add_u32 s76, s36, 0x40000
	s_addc_u32 s77, s37, 0
	s_add_i32 s75, s68, s41
	global_load_lds_dwordx4 v150, s[36:37]
	s_mov_b32 m0, s75
	s_nop 0
	global_load_lds_dwordx4 v148, s[76:77]
	s_add_i32 m0, s75, 0x2000
	s_nop 0
	global_load_lds_dwordx4 v150, s[76:77]
	s_mov_b32 m0, s31
	s_nop 0
	global_load_lds_dwordx4 v148, s[38:39]
	s_mov_b32 m0, s42
	s_nop 0
	global_load_lds_dwordx4 v150, s[38:39]
	s_cmp_lg_u32 s32, 0
	s_cbranch_scc1 .Lpw1b
	s_waitcnt vmcnt(8)
.Lpw1b:
	s_mov_b32 s32, 1
	s_waitcnt lgkmcnt(0)
	s_barrier
	s_setprio 1
	s_waitcnt lgkmcnt(0)
	v_mfma_i32_16x16x64_i8 v[62:65], v[106:109], v[212:215], v[62:65]
	v_mfma_i32_16x16x64_i8 v[58:61], v[114:117], v[212:215], v[58:61]
	v_mfma_i32_16x16x64_i8 v[46:49], v[106:109], v[220:223], v[46:49]
	v_mfma_i32_16x16x64_i8 v[42:45], v[114:117], v[220:223], v[42:45]
	v_mfma_i32_16x16x64_i8 v[30:33], v[106:109], v[228:231], v[30:33]
	v_mfma_i32_16x16x64_i8 v[26:29], v[114:117], v[228:231], v[26:29]
	v_mfma_i32_16x16x64_i8 v[14:17], v[106:109], v[236:239], v[14:17]
	v_mfma_i32_16x16x64_i8 v[10:13], v[114:117], v[236:239], v[10:13]
	v_mfma_i32_16x16x64_i8 v[62:65], v[110:113], v[216:219], v[62:65]
	v_mfma_i32_16x16x64_i8 v[58:61], v[118:121], v[216:219], v[58:61]
	v_mfma_i32_16x16x64_i8 v[46:49], v[110:113], v[224:227], v[46:49]
	v_mfma_i32_16x16x64_i8 v[42:45], v[118:121], v[224:227], v[42:45]
	v_mfma_i32_16x16x64_i8 v[30:33], v[110:113], v[232:235], v[30:33]
	v_mfma_i32_16x16x64_i8 v[26:29], v[118:121], v[232:235], v[26:29]
	v_mfma_i32_16x16x64_i8 v[14:17], v[110:113], v[240:243], v[14:17]
	v_mfma_i32_16x16x64_i8 v[10:13], v[118:121], v[240:243], v[10:13]
	s_setprio 0
	s_setprio 1
	v_mfma_i32_16x16x64_i8 v[54:57], v[174:177], v[212:215], v[54:57]
	v_mfma_i32_16x16x64_i8 v[50:53], v[204:207], v[212:215], v[50:53]
	v_mfma_i32_16x16x64_i8 v[38:41], v[174:177], v[220:223], v[38:41]
	v_mfma_i32_16x16x64_i8 v[34:37], v[204:207], v[220:223], v[34:37]
	v_mfma_i32_16x16x64_i8 v[22:25], v[174:177], v[228:231], v[22:25]
	v_mfma_i32_16x16x64_i8 v[18:21], v[204:207], v[228:231], v[18:21]
	v_mfma_i32_16x16x64_i8 v[6:9], v[174:177], v[236:239], v[6:9]
	v_mfma_i32_16x16x64_i8 v[2:5], v[204:207], v[236:239], v[2:5]
	v_mfma_i32_16x16x64_i8 v[54:57], v[200:203], v[216:219], v[54:57]
	v_mfma_i32_16x16x64_i8 v[50:53], v[208:211], v[216:219], v[50:53]
	v_mfma_i32_16x16x64_i8 v[38:41], v[200:203], v[224:227], v[38:41]
	v_mfma_i32_16x16x64_i8 v[34:37], v[208:211], v[224:227], v[34:37]
	v_mfma_i32_16x16x64_i8 v[22:25], v[200:203], v[232:235], v[22:25]
	v_mfma_i32_16x16x64_i8 v[18:21], v[208:211], v[232:235], v[18:21]
	v_mfma_i32_16x16x64_i8 v[6:9], v[200:203], v[240:243], v[6:9]
	v_mfma_i32_16x16x64_i8 v[2:5], v[208:211], v[240:243], v[2:5]
	s_setprio 0
	s_barrier
	s_add_i32 s75, 0, 0x18000
	s_add_i32 s76, 0, 0x1c000
	v_add_u32_e32 v118, s75, v195
	v_add_u32_e32 v164, s76, v195
	ds_read_b128 v[106:109], v118
	ds_read_b128 v[110:113], v118 offset:1024
	ds_read_b128 v[114:117], v118 offset:2048
	ds_read_b128 v[118:121], v118 offset:3072
	ds_read_b128 v[174:177], v164
	ds_read_b128 v[200:203], v164 offset:1024
	ds_read_b128 v[204:207], v164 offset:2048
	ds_read_b128 v[208:211], v164 offset:3072
	s_add_u32 s38, s38, 0x40000
	s_addc_u32 s39, s39, 0
	s_mov_b32 m0, s43
	ds_read_b128 v[212:215], v198 offset:32768
	ds_read_b128 v[216:219], v198 offset:33792
	ds_read_b128 v[220:223], v198 offset:34816
	ds_read_b128 v[224:227], v198 offset:35840
	ds_read_b128 v[228:231], v198 offset:36864
	ds_read_b128 v[232:235], v198 offset:37888
	ds_read_b128 v[236:239], v198 offset:38912
	ds_read_b128 v[240:243], v198 offset:39936
	global_load_lds_dwordx4 v148, s[38:39]
	s_mov_b32 m0, s46
	s_nop 0
	global_load_lds_dwordx4 v150, s[38:39]
	s_waitcnt vmcnt(8)
	s_waitcnt lgkmcnt(0)
	s_barrier
	s_setprio 1
	s_waitcnt lgkmcnt(0)
	v_mfma_i32_16x16x64_i8 v[142:145], v[106:109], v[212:215], v[142:145]
	v_mfma_i32_16x16x64_i8 v[138:141], v[114:117], v[212:215], v[138:141]
	v_mfma_i32_16x16x64_i8 v[126:129], v[106:109], v[220:223], v[126:129]
	v_mfma_i32_16x16x64_i8 v[122:125], v[114:117], v[220:223], v[122:125]
	v_mfma_i32_16x16x64_i8 v[94:97], v[106:109], v[228:231], v[94:97]
	v_mfma_i32_16x16x64_i8 v[90:93], v[114:117], v[228:231], v[90:93]
	v_mfma_i32_16x16x64_i8 v[78:81], v[106:109], v[236:239], v[78:81]
	v_mfma_i32_16x16x64_i8 v[74:77], v[114:117], v[236:239], v[74:77]
	v_mfma_i32_16x16x64_i8 v[142:145], v[110:113], v[216:219], v[142:145]
	v_mfma_i32_16x16x64_i8 v[138:141], v[118:121], v[216:219], v[138:141]
	v_mfma_i32_16x16x64_i8 v[126:129], v[110:113], v[224:227], v[126:129]
	v_mfma_i32_16x16x64_i8 v[122:125], v[118:121], v[224:227], v[122:125]
	v_mfma_i32_16x16x64_i8 v[94:97], v[110:113], v[232:235], v[94:97]
	v_mfma_i32_16x16x64_i8 v[90:93], v[118:121], v[232:235], v[90:93]
	v_mfma_i32_16x16x64_i8 v[78:81], v[110:113], v[240:243], v[78:81]
	v_mfma_i32_16x16x64_i8 v[74:77], v[118:121], v[240:243], v[74:77]
	s_setprio 0
	s_setprio 1
	v_mfma_i32_16x16x64_i8 v[134:137], v[174:177], v[212:215], v[134:137]
	v_mfma_i32_16x16x64_i8 v[130:133], v[204:207], v[212:215], v[130:133]
	v_mfma_i32_16x16x64_i8 v[102:105], v[174:177], v[220:223], v[102:105]
	v_mfma_i32_16x16x64_i8 v[98:101], v[204:207], v[220:223], v[98:101]
	v_mfma_i32_16x16x64_i8 v[86:89], v[174:177], v[228:231], v[86:89]
	v_mfma_i32_16x16x64_i8 v[82:85], v[204:207], v[228:231], v[82:85]
	v_mfma_i32_16x16x64_i8 v[70:73], v[174:177], v[236:239], v[70:73]
	v_mfma_i32_16x16x64_i8 v[66:69], v[204:207], v[236:239], v[66:69]
	v_mfma_i32_16x16x64_i8 v[134:137], v[200:203], v[216:219], v[134:137]
	v_mfma_i32_16x16x64_i8 v[130:133], v[208:211], v[216:219], v[130:133]
	v_mfma_i32_16x16x64_i8 v[102:105], v[200:203], v[224:227], v[102:105]
	v_mfma_i32_16x16x64_i8 v[98:101], v[208:211], v[224:227], v[98:101]
	v_mfma_i32_16x16x64_i8 v[86:89], v[200:203], v[232:235], v[86:89]
	v_mfma_i32_16x16x64_i8 v[82:85], v[208:211], v[232:235], v[82:85]
	v_mfma_i32_16x16x64_i8 v[70:73], v[200:203], v[240:243], v[70:73]
	v_mfma_i32_16x16x64_i8 v[66:69], v[208:211], v[240:243], v[66:69]
	s_setprio 0
	s_barrier
	s_add_u32 s98, s38, 0xfffc0080
	s_addc_u32 s99, s39, -1
	s_add_i32 s38, s75, s41
	s_mov_b32 m0, s38
	ds_read_b128 v[212:215], v198 offset:49152
	ds_read_b128 v[216:219], v198 offset:50176
	ds_read_b128 v[220:223], v198 offset:51200
	ds_read_b128 v[224:227], v198 offset:52224
	ds_read_b128 v[228:231], v198 offset:53248
	ds_read_b128 v[232:235], v198 offset:54272
	ds_read_b128 v[236:239], v198 offset:55296
	ds_read_b128 v[240:243], v198 offset:56320
	s_add_u32 s100, s36, 0x80
	s_addc_u32 s101, s37, 0
	global_load_lds_dwordx4 v148, s[100:101]
	s_add_i32 m0, s38, 0x2000
	s_add_u32 s36, s36, 0x40080
	s_addc_u32 s37, s37, 0
	s_add_i32 s38, s76, s41
	global_load_lds_dwordx4 v150, s[100:101]
	s_mov_b32 m0, s38
	s_nop 0
	global_load_lds_dwordx4 v148, s[36:37]
	s_add_i32 m0, s38, 0x2000
	s_nop 0
	global_load_lds_dwordx4 v150, s[36:37]
	s_mov_b32 m0, s56
	s_nop 0
	global_load_lds_dwordx4 v148, s[98:99]
	s_mov_b32 m0, s57
	s_nop 0
	global_load_lds_dwordx4 v150, s[98:99]
	s_waitcnt vmcnt(8)
	s_waitcnt lgkmcnt(0)
	s_barrier
	s_setprio 1
	s_waitcnt lgkmcnt(0)
	v_mfma_i32_16x16x64_i8 v[62:65], v[106:109], v[212:215], v[62:65]
	v_mfma_i32_16x16x64_i8 v[58:61], v[114:117], v[212:215], v[58:61]
	v_mfma_i32_16x16x64_i8 v[46:49], v[106:109], v[220:223], v[46:49]
	v_mfma_i32_16x16x64_i8 v[42:45], v[114:117], v[220:223], v[42:45]
	v_mfma_i32_16x16x64_i8 v[30:33], v[106:109], v[228:231], v[30:33]
	v_mfma_i32_16x16x64_i8 v[26:29], v[114:117], v[228:231], v[26:29]
	v_mfma_i32_16x16x64_i8 v[14:17], v[106:109], v[236:239], v[14:17]
	v_mfma_i32_16x16x64_i8 v[10:13], v[114:117], v[236:239], v[10:13]
	v_mfma_i32_16x16x64_i8 v[62:65], v[110:113], v[216:219], v[62:65]
	v_mfma_i32_16x16x64_i8 v[58:61], v[118:121], v[216:219], v[58:61]
	v_mfma_i32_16x16x64_i8 v[46:49], v[110:113], v[224:227], v[46:49]
	v_mfma_i32_16x16x64_i8 v[42:45], v[118:121], v[224:227], v[42:45]
	v_mfma_i32_16x16x64_i8 v[30:33], v[110:113], v[232:235], v[30:33]
	v_mfma_i32_16x16x64_i8 v[26:29], v[118:121], v[232:235], v[26:29]
	v_mfma_i32_16x16x64_i8 v[14:17], v[110:113], v[240:243], v[14:17]
	v_mfma_i32_16x16x64_i8 v[10:13], v[118:121], v[240:243], v[10:13]
	s_setprio 0
	s_setprio 1
	v_mfma_i32_16x16x64_i8 v[54:57], v[174:177], v[212:215], v[54:57]
	v_mfma_i32_16x16x64_i8 v[50:53], v[204:207], v[212:215], v[50:53]
	v_mfma_i32_16x16x64_i8 v[38:41], v[174:177], v[220:223], v[38:41]
	v_mfma_i32_16x16x64_i8 v[34:37], v[204:207], v[220:223], v[34:37]
	v_mfma_i32_16x16x64_i8 v[22:25], v[174:177], v[228:231], v[22:25]
	v_mfma_i32_16x16x64_i8 v[18:21], v[204:207], v[228:231], v[18:21]
	v_mfma_i32_16x16x64_i8 v[6:9], v[174:177], v[236:239], v[6:9]
	v_mfma_i32_16x16x64_i8 v[2:5], v[204:207], v[236:239], v[2:5]
	v_mfma_i32_16x16x64_i8 v[54:57], v[200:203], v[216:219], v[54:57]
	v_mfma_i32_16x16x64_i8 v[50:53], v[208:211], v[216:219], v[50:53]
	v_mfma_i32_16x16x64_i8 v[38:41], v[200:203], v[224:227], v[38:41]
	v_mfma_i32_16x16x64_i8 v[34:37], v[208:211], v[224:227], v[34:37]
	v_mfma_i32_16x16x64_i8 v[22:25], v[200:203], v[232:235], v[22:25]
	v_mfma_i32_16x16x64_i8 v[18:21], v[208:211], v[232:235], v[18:21]
	v_mfma_i32_16x16x64_i8 v[6:9], v[200:203], v[240:243], v[6:9]
	v_mfma_i32_16x16x64_i8 v[2:5], v[208:211], v[240:243], v[2:5]
	s_setprio 0
	s_barrier
	s_add_i32 s74, s74, 2
	s_add_u32 s34, s34, 0x100
	s_addc_u32 s35, s35, 0
	s_add_u32 s72, s72, 0x100
	s_addc_u32 s73, s73, 0
	s_cmp_gt_u32 s74, 13

.LBB0_557:
	s_mov_b32 s32, 0
	s_andn2_b64 vcc, exec, s[0:1]
	v_readfirstlane_b32 s3, v0
	s_cbranch_vccnz .LBB0_581
	s_ashr_i32 s28, s33, 31
	s_lshr_b32 s0, s28, 29
	s_add_i32 s2, s33, s0
	s_and_b32 s0, s2, -8
	s_sub_i32 s4, s33, s0
	s_cmp_gt_i32 s4, -1
	s_cbranch_scc0 .LBB0_560
	s_lshl_b32 s5, s4, 7
	s_cbranch_execz .LBB0_561
	s_branch .LBB0_562

.LBB0_573:
	s_ashr_i32 s13, s12, 31
	s_lshl_b64 s[14:15], s[12:13], 18
	s_add_u32 s14, s30, s14
	s_addc_u32 s15, s31, s15
	s_and_b64 s[16:17], s[2:3], exec
	s_cselect_b32 s13, s15, s23
	s_cselect_b32 s46, s14, s22
	s_ashr_i32 s11, s10, 31
	s_lshl_b64 s[16:17], s[10:11], 18
	v_readlane_b32 s68, v254, 4
	s_add_u32 s16, s68, s16
	s_addc_u32 s17, s78, s17
	s_and_b64 s[26:27], s[2:3], exec
	s_cselect_b32 s11, s17, s25
	s_cselect_b32 s47, s16, s24
	s_add_u32 s22, s22, 0x20080
	s_addc_u32 s23, s23, 0
	s_add_u32 s56, s24, 0x100
	v_mov_b32_e32 v2, 0
	s_addc_u32 s57, s25, 0
	s_mov_b32 s66, -2
	v_mov_b32_e32 v3, v2
	v_mov_b32_e32 v4, v2
	v_mov_b32_e32 v5, v2
	v_mov_b32_e32 v6, v2
	v_mov_b32_e32 v7, v2
	v_mov_b32_e32 v8, v2
	v_mov_b32_e32 v9, v2
	v_mov_b32_e32 v18, v2
	v_mov_b32_e32 v19, v2
	v_mov_b32_e32 v20, v2
	v_mov_b32_e32 v21, v2
	v_mov_b32_e32 v22, v2
	v_mov_b32_e32 v23, v2
	v_mov_b32_e32 v24, v2
	v_mov_b32_e32 v25, v2
	v_mov_b32_e32 v34, v2
	v_mov_b32_e32 v35, v2
	v_mov_b32_e32 v36, v2
	v_mov_b32_e32 v37, v2
	v_mov_b32_e32 v38, v2
	v_mov_b32_e32 v39, v2
	v_mov_b32_e32 v40, v2
	v_mov_b32_e32 v41, v2
	s_waitcnt vmcnt(0)
	v_mov_b32_e32 v50, v2
	v_mov_b32_e32 v51, v2
	v_mov_b32_e32 v52, v2
	v_mov_b32_e32 v53, v2
	v_mov_b32_e32 v54, v2
	v_mov_b32_e32 v55, v2
	v_mov_b32_e32 v56, v2
	v_mov_b32_e32 v57, v2
	v_mov_b32_e32 v10, v2
	v_mov_b32_e32 v11, v2
	v_mov_b32_e32 v12, v2
	v_mov_b32_e32 v13, v2
	v_mov_b32_e32 v14, v2
	v_mov_b32_e32 v15, v2
	v_mov_b32_e32 v16, v2
	v_mov_b32_e32 v17, v2
	v_mov_b32_e32 v26, v2
	v_mov_b32_e32 v27, v2
	v_mov_b32_e32 v28, v2
	v_mov_b32_e32 v29, v2
	v_mov_b32_e32 v30, v2
	v_mov_b32_e32 v31, v2
	v_mov_b32_e32 v32, v2
	v_mov_b32_e32 v33, v2
	v_mov_b32_e32 v42, v2
	v_mov_b32_e32 v43, v2
	v_mov_b32_e32 v44, v2
	v_mov_b32_e32 v45, v2
	v_mov_b32_e32 v46, v2
	v_mov_b32_e32 v47, v2
	v_mov_b32_e32 v48, v2
	v_mov_b32_e32 v49, v2
	v_mov_b32_e32 v58, v2
	v_mov_b32_e32 v59, v2
	v_mov_b32_e32 v60, v2
	v_mov_b32_e32 v61, v2
	v_mov_b32_e32 v62, v2
	v_mov_b32_e32 v63, v2
	v_mov_b32_e32 v64, v2
	v_mov_b32_e32 v65, v2
	v_mov_b32_e32 v66, v2
	v_mov_b32_e32 v67, v2
	v_mov_b32_e32 v68, v2
	v_mov_b32_e32 v69, v2
	v_mov_b32_e32 v70, v2
	v_mov_b32_e32 v71, v2
	v_mov_b32_e32 v72, v2
	v_mov_b32_e32 v73, v2
	v_mov_b32_e32 v82, v2
	v_mov_b32_e32 v83, v2
	v_mov_b32_e32 v84, v2
	v_mov_b32_e32 v85, v2
	v_mov_b32_e32 v86, v2
	v_mov_b32_e32 v87, v2
	v_mov_b32_e32 v88, v2
	v_mov_b32_e32 v89, v2
	v_mov_b32_e32 v114, v2
	v_mov_b32_e32 v115, v2
	v_mov_b32_e32 v116, v2
	v_mov_b32_e32 v117, v2
	v_mov_b32_e32 v118, v2
	v_mov_b32_e32 v119, v2
	v_mov_b32_e32 v120, v2
	v_mov_b32_e32 v121, v2
	v_mov_b32_e32 v130, v2
	v_mov_b32_e32 v131, v2
	v_mov_b32_e32 v132, v2
	v_mov_b32_e32 v133, v2
	v_mov_b32_e32 v134, v2
	v_mov_b32_e32 v135, v2
	v_mov_b32_e32 v136, v2
	v_mov_b32_e32 v137, v2
	v_mov_b32_e32 v74, v2
	v_mov_b32_e32 v75, v2
	v_mov_b32_e32 v76, v2
	v_mov_b32_e32 v77, v2
	v_mov_b32_e32 v78, v2
	v_mov_b32_e32 v79, v2
	v_mov_b32_e32 v80, v2
	v_mov_b32_e32 v81, v2
	v_mov_b32_e32 v106, v2
	v_mov_b32_e32 v107, v2
	v_mov_b32_e32 v108, v2
	v_mov_b32_e32 v109, v2
	v_mov_b32_e32 v110, v2
	v_mov_b32_e32 v111, v2
	v_mov_b32_e32 v112, v2
	v_mov_b32_e32 v113, v2
	v_mov_b32_e32 v122, v2
	v_mov_b32_e32 v123, v2
	v_mov_b32_e32 v124, v2
	v_mov_b32_e32 v125, v2
	v_mov_b32_e32 v126, v2
	v_mov_b32_e32 v127, v2
	v_mov_b32_e32 v128, v2
	v_mov_b32_e32 v129, v2
	v_mov_b32_e32 v138, v2
	v_mov_b32_e32 v139, v2
	v_mov_b32_e32 v140, v2
	v_mov_b32_e32 v141, v2
	v_mov_b32_e32 v94, v2
	v_mov_b32_e32 v95, v2
	v_mov_b32_e32 v96, v2
	v_mov_b32_e32 v97, v2
	v_readlane_b32 s69, v254, 5
	v_readlane_b32 s70, v254, 6
	v_readlane_b32 s71, v254, 7
	ds_read_b128 v[90:93], v1
	ds_read_b128 v[98:101], v1 offset:1024
	ds_read_b128 v[102:105], v1 offset:2048
	ds_read_b128 v[142:145], v1 offset:3072
	ds_read_b128 v[146:149], v203
	ds_read_b128 v[150:153], v203 offset:1024
	ds_read_b128 v[154:157], v203 offset:2048
	ds_read_b128 v[158:161], v203 offset:3072
	s_add_u32 s24, s22, 0xfffe0080
	s_addc_u32 s25, s23, -1
	s_cmp_eq_u32 s66, 4
	s_cselect_b32 s27, s13, s25
	s_cselect_b32 s26, s46, s24
	s_cselect_b32 s25, s11, s57
	s_cselect_b32 s24, s47, s56
	s_add_i32 m0, s19, 0xc000
	ds_read_b128 v[162:165], v205
	ds_read_b128 v[166:169], v205 offset:1024
	ds_read_b128 v[170:173], v205 offset:2048
	ds_read_b128 v[174:177], v205 offset:3072
	ds_read_b128 v[178:181], v205 offset:4096
	ds_read_b128 v[206:209], v205 offset:5120
	ds_read_b128 v[210:213], v205 offset:6144
	ds_read_b128 v[214:217], v205 offset:7168
	global_load_lds_dwordx4 v190, s[22:23]
	s_add_i32 m0, s19, 0xe000
	s_nop 0
	global_load_lds_dwordx4 v192, s[22:23]
	s_cmp_lg_u32 s32, 0
	s_cbranch_scc1 .Lpw2a
	s_waitcnt vmcnt(8)
.Lpw2a:
	s_waitcnt lgkmcnt(0)
	s_barrier
	s_setprio 1
	s_waitcnt lgkmcnt(0)
	v_mfma_i32_16x16x64_i8 v[94:97], v[90:93], v[162:165], v[94:97]
	v_mfma_i32_16x16x64_i8 v[138:141], v[102:105], v[162:165], v[138:141]
	v_mfma_i32_16x16x64_i8 v[126:129], v[90:93], v[170:173], v[126:129]
	v_mfma_i32_16x16x64_i8 v[122:125], v[102:105], v[170:173], v[122:125]
	v_mfma_i32_16x16x64_i8 v[110:113], v[90:93], v[178:181], v[110:113]
	v_mfma_i32_16x16x64_i8 v[106:109], v[102:105], v[178:181], v[106:109]
	v_mfma_i32_16x16x64_i8 v[78:81], v[90:93], v[210:213], v[78:81]
	v_mfma_i32_16x16x64_i8 v[74:77], v[102:105], v[210:213], v[74:77]
	v_mfma_i32_16x16x64_i8 v[94:97], v[98:101], v[166:169], v[94:97]
	v_mfma_i32_16x16x64_i8 v[138:141], v[142:145], v[166:169], v[138:141]
	v_mfma_i32_16x16x64_i8 v[126:129], v[98:101], v[174:177], v[126:129]
	v_mfma_i32_16x16x64_i8 v[122:125], v[142:145], v[174:177], v[122:125]
	v_mfma_i32_16x16x64_i8 v[110:113], v[98:101], v[206:209], v[110:113]
	v_mfma_i32_16x16x64_i8 v[106:109], v[142:145], v[206:209], v[106:109]
	v_mfma_i32_16x16x64_i8 v[78:81], v[98:101], v[214:217], v[78:81]
	v_mfma_i32_16x16x64_i8 v[74:77], v[142:145], v[214:217], v[74:77]
	s_setprio 0
	s_setprio 1
	v_mfma_i32_16x16x64_i8 v[134:137], v[146:149], v[162:165], v[134:137]
	v_mfma_i32_16x16x64_i8 v[130:133], v[154:157], v[162:165], v[130:133]
	v_mfma_i32_16x16x64_i8 v[118:121], v[146:149], v[170:173], v[118:121]
	v_mfma_i32_16x16x64_i8 v[114:117], v[154:157], v[170:173], v[114:117]
	v_mfma_i32_16x16x64_i8 v[86:89], v[146:149], v[178:181], v[86:89]
	v_mfma_i32_16x16x64_i8 v[82:85], v[154:157], v[178:181], v[82:85]
	v_mfma_i32_16x16x64_i8 v[70:73], v[146:149], v[210:213], v[70:73]
	v_mfma_i32_16x16x64_i8 v[66:69], v[154:157], v[210:213], v[66:69]
	v_mfma_i32_16x16x64_i8 v[134:137], v[150:153], v[166:169], v[134:137]
	v_mfma_i32_16x16x64_i8 v[130:133], v[158:161], v[166:169], v[130:133]
	v_mfma_i32_16x16x64_i8 v[118:121], v[150:153], v[174:177], v[118:121]
	v_mfma_i32_16x16x64_i8 v[114:117], v[158:161], v[174:177], v[114:117]
	v_mfma_i32_16x16x64_i8 v[86:89], v[150:153], v[206:209], v[86:89]
	v_mfma_i32_16x16x64_i8 v[82:85], v[158:161], v[206:209], v[82:85]
	v_mfma_i32_16x16x64_i8 v[70:73], v[150:153], v[214:217], v[70:73]
	v_mfma_i32_16x16x64_i8 v[66:69], v[158:161], v[214:217], v[66:69]
	s_setprio 0
	s_barrier
	s_add_i32 s67, s41, s29
	s_mov_b32 m0, s67
	ds_read_b128 v[162:165], v205 offset:16384
	ds_read_b128 v[166:169], v205 offset:17408
	ds_read_b128 v[170:173], v205 offset:18432
	ds_read_b128 v[174:177], v205 offset:19456
	ds_read_b128 v[178:181], v205 offset:20480
	ds_read_b128 v[206:209], v205 offset:21504
	ds_read_b128 v[210:213], v205 offset:22528
	ds_read_b128 v[214:217], v205 offset:23552
	global_load_lds_dwordx4 v184, s[24:25]
	s_add_i32 m0, s67, 0x2000
	s_add_u32 s68, s24, 0x20000
	s_addc_u32 s69, s25, 0
	s_add_i32 s67, s42, s29
	global_load_lds_dwordx4 v186, s[24:25]
	s_mov_b32 m0, s67
	s_nop 0
	global_load_lds_dwordx4 v184, s[68:69]
	s_add_i32 m0, s67, 0x2000
	s_nop 0
	global_load_lds_dwordx4 v186, s[68:69]
	s_mov_b32 m0, s19
	s_nop 0
	global_load_lds_dwordx4 v184, s[26:27]
	s_mov_b32 m0, s34
	s_nop 0
	global_load_lds_dwordx4 v186, s[26:27]
	s_cmp_lg_u32 s32, 0
	s_cbranch_scc1 .Lpw2b
	s_waitcnt vmcnt(8)
.Lpw2b:
	s_mov_b32 s32, 1
	s_waitcnt lgkmcnt(0)
	s_barrier
	s_setprio 1
	s_waitcnt lgkmcnt(0)
	v_mfma_i32_16x16x64_i8 v[62:65], v[90:93], v[162:165], v[62:65]
	v_mfma_i32_16x16x64_i8 v[58:61], v[102:105], v[162:165], v[58:61]
	v_mfma_i32_16x16x64_i8 v[46:49], v[90:93], v[170:173], v[46:49]
	v_mfma_i32_16x16x64_i8 v[42:45], v[102:105], v[170:173], v[42:45]
	v_mfma_i32_16x16x64_i8 v[30:33], v[90:93], v[178:181], v[30:33]
	v_mfma_i32_16x16x64_i8 v[26:29], v[102:105], v[178:181], v[26:29]
	v_mfma_i32_16x16x64_i8 v[14:17], v[90:93], v[210:213], v[14:17]
	v_mfma_i32_16x16x64_i8 v[10:13], v[102:105], v[210:213], v[10:13]
	v_mfma_i32_16x16x64_i8 v[62:65], v[98:101], v[166:169], v[62:65]
	v_mfma_i32_16x16x64_i8 v[58:61], v[142:145], v[166:169], v[58:61]
	v_mfma_i32_16x16x64_i8 v[46:49], v[98:101], v[174:177], v[46:49]
	v_mfma_i32_16x16x64_i8 v[42:45], v[142:145], v[174:177], v[42:45]
	v_mfma_i32_16x16x64_i8 v[30:33], v[98:101], v[206:209], v[30:33]
	v_mfma_i32_16x16x64_i8 v[26:29], v[142:145], v[206:209], v[26:29]
	v_mfma_i32_16x16x64_i8 v[14:17], v[98:101], v[214:217], v[14:17]
	v_mfma_i32_16x16x64_i8 v[10:13], v[142:145], v[214:217], v[10:13]
	s_setprio 0
	s_setprio 1
	v_mfma_i32_16x16x64_i8 v[54:57], v[146:149], v[162:165], v[54:57]
	v_mfma_i32_16x16x64_i8 v[50:53], v[154:157], v[162:165], v[50:53]
	v_mfma_i32_16x16x64_i8 v[38:41], v[146:149], v[170:173], v[38:41]
	v_mfma_i32_16x16x64_i8 v[34:37], v[154:157], v[170:173], v[34:37]
	v_mfma_i32_16x16x64_i8 v[22:25], v[146:149], v[178:181], v[22:25]
	v_mfma_i32_16x16x64_i8 v[18:21], v[154:157], v[178:181], v[18:21]
	v_mfma_i32_16x16x64_i8 v[6:9], v[146:149], v[210:213], v[6:9]
	v_mfma_i32_16x16x64_i8 v[2:5], v[154:157], v[210:213], v[2:5]
	v_mfma_i32_16x16x64_i8 v[54:57], v[150:153], v[166:169], v[54:57]
	v_mfma_i32_16x16x64_i8 v[50:53], v[158:161], v[166:169], v[50:53]
	v_mfma_i32_16x16x64_i8 v[38:41], v[150:153], v[174:177], v[38:41]
	v_mfma_i32_16x16x64_i8 v[34:37], v[158:161], v[174:177], v[34:37]
	v_mfma_i32_16x16x64_i8 v[22:25], v[150:153], v[206:209], v[22:25]
	v_mfma_i32_16x16x64_i8 v[18:21], v[158:161], v[206:209], v[18:21]
	v_mfma_i32_16x16x64_i8 v[6:9], v[150:153], v[214:217], v[6:9]
	v_mfma_i32_16x16x64_i8 v[2:5], v[158:161], v[214:217], v[2:5]
	s_setprio 0
	s_barrier
	s_add_i32 s67, 0, 0x18000
	s_add_i32 s68, 0, 0x1c000
	v_add_u32_e32 v142, s67, v183
	v_add_u32_e32 v158, s68, v183
	ds_read_b128 v[90:93], v142
	ds_read_b128 v[98:101], v142 offset:1024
	ds_read_b128 v[102:105], v142 offset:2048
	ds_read_b128 v[142:145], v142 offset:3072
	ds_read_b128 v[146:149], v158
	ds_read_b128 v[150:153], v158 offset:1024
	ds_read_b128 v[154:157], v158 offset:2048
	ds_read_b128 v[158:161], v158 offset:3072
	s_add_u32 s26, s26, 0x20000
	s_addc_u32 s27, s27, 0
	s_mov_b32 m0, s35
	ds_read_b128 v[162:165], v205 offset:32768
	ds_read_b128 v[166:169], v205 offset:33792
	ds_read_b128 v[170:173], v205 offset:34816
	ds_read_b128 v[174:177], v205 offset:35840
	ds_read_b128 v[178:181], v205 offset:36864
	ds_read_b128 v[206:209], v205 offset:37888
	ds_read_b128 v[210:213], v205 offset:38912
	ds_read_b128 v[214:217], v205 offset:39936
	global_load_lds_dwordx4 v184, s[26:27]
	s_mov_b32 m0, s36
	s_nop 0
	global_load_lds_dwordx4 v186, s[26:27]
	s_waitcnt vmcnt(8)
	s_waitcnt lgkmcnt(0)
	s_barrier
	s_setprio 1
	s_waitcnt lgkmcnt(0)
	v_mfma_i32_16x16x64_i8 v[94:97], v[90:93], v[162:165], v[94:97]
	v_mfma_i32_16x16x64_i8 v[138:141], v[102:105], v[162:165], v[138:141]
	v_mfma_i32_16x16x64_i8 v[126:129], v[90:93], v[170:173], v[126:129]
	v_mfma_i32_16x16x64_i8 v[122:125], v[102:105], v[170:173], v[122:125]
	v_mfma_i32_16x16x64_i8 v[110:113], v[90:93], v[178:181], v[110:113]
	v_mfma_i32_16x16x64_i8 v[106:109], v[102:105], v[178:181], v[106:109]
	v_mfma_i32_16x16x64_i8 v[78:81], v[90:93], v[210:213], v[78:81]
	v_mfma_i32_16x16x64_i8 v[74:77], v[102:105], v[210:213], v[74:77]
	v_mfma_i32_16x16x64_i8 v[94:97], v[98:101], v[166:169], v[94:97]
	v_mfma_i32_16x16x64_i8 v[138:141], v[142:145], v[166:169], v[138:141]
	v_mfma_i32_16x16x64_i8 v[126:129], v[98:101], v[174:177], v[126:129]
	v_mfma_i32_16x16x64_i8 v[122:125], v[142:145], v[174:177], v[122:125]
	v_mfma_i32_16x16x64_i8 v[110:113], v[98:101], v[206:209], v[110:113]
	v_mfma_i32_16x16x64_i8 v[106:109], v[142:145], v[206:209], v[106:109]
	v_mfma_i32_16x16x64_i8 v[78:81], v[98:101], v[214:217], v[78:81]
	v_mfma_i32_16x16x64_i8 v[74:77], v[142:145], v[214:217], v[74:77]
	s_setprio 0
	s_setprio 1
	v_mfma_i32_16x16x64_i8 v[134:137], v[146:149], v[162:165], v[134:137]
	v_mfma_i32_16x16x64_i8 v[130:133], v[154:157], v[162:165], v[130:133]
	v_mfma_i32_16x16x64_i8 v[118:121], v[146:149], v[170:173], v[118:121]
	v_mfma_i32_16x16x64_i8 v[114:117], v[154:157], v[170:173], v[114:117]
	v_mfma_i32_16x16x64_i8 v[86:89], v[146:149], v[178:181], v[86:89]
	v_mfma_i32_16x16x64_i8 v[82:85], v[154:157], v[178:181], v[82:85]
	v_mfma_i32_16x16x64_i8 v[70:73], v[146:149], v[210:213], v[70:73]
	v_mfma_i32_16x16x64_i8 v[66:69], v[154:157], v[210:213], v[66:69]
	v_mfma_i32_16x16x64_i8 v[134:137], v[150:153], v[166:169], v[134:137]
	v_mfma_i32_16x16x64_i8 v[130:133], v[158:161], v[166:169], v[130:133]
	v_mfma_i32_16x16x64_i8 v[118:121], v[150:153], v[174:177], v[118:121]
	v_mfma_i32_16x16x64_i8 v[114:117], v[158:161], v[174:177], v[114:117]
	v_mfma_i32_16x16x64_i8 v[86:89], v[150:153], v[206:209], v[86:89]
	v_mfma_i32_16x16x64_i8 v[82:85], v[158:161], v[206:209], v[82:85]
	v_mfma_i32_16x16x64_i8 v[70:73], v[150:153], v[214:217], v[70:73]
	v_mfma_i32_16x16x64_i8 v[66:69], v[158:161], v[214:217], v[66:69]
	s_setprio 0
	s_barrier
	s_add_u32 s98, s26, 0xfffe0080
	s_addc_u32 s99, s27, -1
	s_add_i32 s26, s67, s29
	s_mov_b32 m0, s26
	ds_read_b128 v[162:165], v205 offset:49152
	ds_read_b128 v[166:169], v205 offset:50176
	ds_read_b128 v[170:173], v205 offset:51200
	ds_read_b128 v[174:177], v205 offset:52224
	ds_read_b128 v[178:181], v205 offset:53248
	ds_read_b128 v[206:209], v205 offset:54272
	ds_read_b128 v[210:213], v205 offset:55296
	ds_read_b128 v[214:217], v205 offset:56320
	s_add_u32 s100, s24, 0x80
	s_addc_u32 s101, s25, 0
	global_load_lds_dwordx4 v184, s[100:101]
	s_add_i32 m0, s26, 0x2000
	s_add_u32 s24, s24, 0x20080
	s_addc_u32 s25, s25, 0
	s_add_i32 s26, s68, s29
	global_load_lds_dwordx4 v186, s[100:101]
	s_mov_b32 m0, s26
	s_nop 0
	global_load_lds_dwordx4 v184, s[24:25]
	s_add_i32 m0, s26, 0x2000
	s_nop 0
	global_load_lds_dwordx4 v186, s[24:25]
	s_mov_b32 m0, s38
	s_nop 0
	global_load_lds_dwordx4 v184, s[98:99]
	s_mov_b32 m0, s39
	s_nop 0
	global_load_lds_dwordx4 v186, s[98:99]
	s_waitcnt vmcnt(8)
	s_waitcnt lgkmcnt(0)
	s_barrier
	s_setprio 1
	s_waitcnt lgkmcnt(0)
	v_mfma_i32_16x16x64_i8 v[62:65], v[90:93], v[162:165], v[62:65]
	v_mfma_i32_16x16x64_i8 v[58:61], v[102:105], v[162:165], v[58:61]
	v_mfma_i32_16x16x64_i8 v[46:49], v[90:93], v[170:173], v[46:49]
	v_mfma_i32_16x16x64_i8 v[42:45], v[102:105], v[170:173], v[42:45]
	v_mfma_i32_16x16x64_i8 v[30:33], v[90:93], v[178:181], v[30:33]
	v_mfma_i32_16x16x64_i8 v[26:29], v[102:105], v[178:181], v[26:29]
	v_mfma_i32_16x16x64_i8 v[14:17], v[90:93], v[210:213], v[14:17]
	v_mfma_i32_16x16x64_i8 v[10:13], v[102:105], v[210:213], v[10:13]
	v_mfma_i32_16x16x64_i8 v[62:65], v[98:101], v[166:169], v[62:65]
	v_mfma_i32_16x16x64_i8 v[58:61], v[142:145], v[166:169], v[58:61]
	v_mfma_i32_16x16x64_i8 v[46:49], v[98:101], v[174:177], v[46:49]
	v_mfma_i32_16x16x64_i8 v[42:45], v[142:145], v[174:177], v[42:45]
	v_mfma_i32_16x16x64_i8 v[30:33], v[98:101], v[206:209], v[30:33]
	v_mfma_i32_16x16x64_i8 v[26:29], v[142:145], v[206:209], v[26:29]
	v_mfma_i32_16x16x64_i8 v[14:17], v[98:101], v[214:217], v[14:17]
	v_mfma_i32_16x16x64_i8 v[10:13], v[142:145], v[214:217], v[10:13]
	s_setprio 0
	s_setprio 1
	v_mfma_i32_16x16x64_i8 v[54:57], v[146:149], v[162:165], v[54:57]
	v_mfma_i32_16x16x64_i8 v[50:53], v[154:157], v[162:165], v[50:53]
	v_mfma_i32_16x16x64_i8 v[38:41], v[146:149], v[170:173], v[38:41]
	v_mfma_i32_16x16x64_i8 v[34:37], v[154:157], v[170:173], v[34:37]
	v_mfma_i32_16x16x64_i8 v[22:25], v[146:149], v[178:181], v[22:25]
	v_mfma_i32_16x16x64_i8 v[18:21], v[154:157], v[178:181], v[18:21]
	v_mfma_i32_16x16x64_i8 v[6:9], v[146:149], v[210:213], v[6:9]
	v_mfma_i32_16x16x64_i8 v[2:5], v[154:157], v[210:213], v[2:5]
	v_mfma_i32_16x16x64_i8 v[54:57], v[150:153], v[166:169], v[54:57]
	v_mfma_i32_16x16x64_i8 v[50:53], v[158:161], v[166:169], v[50:53]
	v_mfma_i32_16x16x64_i8 v[38:41], v[150:153], v[174:177], v[38:41]
	v_mfma_i32_16x16x64_i8 v[34:37], v[158:161], v[174:177], v[34:37]
	v_mfma_i32_16x16x64_i8 v[22:25], v[150:153], v[206:209], v[22:25]
	v_mfma_i32_16x16x64_i8 v[18:21], v[158:161], v[206:209], v[18:21]
	v_mfma_i32_16x16x64_i8 v[6:9], v[150:153], v[214:217], v[6:9]
	v_mfma_i32_16x16x64_i8 v[2:5], v[158:161], v[214:217], v[2:5]
	s_setprio 0
	s_barrier
	s_add_i32 s66, s66, 2
	s_add_u32 s22, s22, 0x100
	s_addc_u32 s23, s23, 0
	s_add_u32 s56, s56, 0x100
	s_addc_u32 s57, s57, 0
	s_cmp_gt_u32 s66, 5

.LBB0_695:
	s_mov_b32 s32, 0
	s_cmp_lt_i32 s88, 8
	s_cselect_b64 s[0:1], -1, 0
	s_cmp_gt_i32 s89, 7
	s_cselect_b64 s[2:3], -1, 0
	s_and_b64 s[0:1], s[0:1], s[2:3]
	s_andn2_b64 vcc, exec, s[0:1]
	s_cbranch_vccnz .LBB0_770
	s_cmpk_gt_i32 s33, 0x3ff
	v_readfirstlane_b32 s2, v0
	s_cbranch_scc1 .LBB0_716
	v_lshlrev_b32_e32 v1, 4, v0
	v_and_b32_e32 v2, 32, v0
	v_or_b32_e32 v13, 0x2000, v1
	v_bfe_u32 v12, v0, 2, 4
	v_bitop3_b32 v10, v1, v2, 48 bitop3:0x6c
	v_lshrrev_b32_e32 v1, 7, v13
	s_movk_i32 s0, 0x70
	s_ashr_i32 s43, s33, 31
	v_and_or_b32 v1, v1, s0, v12
	s_lshr_b32 s0, s43, 29
	s_add_i32 s0, s33, s0
	s_and_b32 s1, s0, -8
	s_lshr_b32 s6, s2, 6
	s_sub_i32 s1, s33, s1
	s_lshr_b32 s3, s2, 8
	s_lshl_b32 s42, s6, 10
	s_lshl_b32 s5, s1, 7
	s_ashr_i32 s0, s0, 3
	s_mul_i32 s4, s1, 0x81
	s_cmp_lt_i32 s1, 0
	s_cselect_b32 s1, s4, s5
	s_add_i32 s0, s1, s0
	s_ashr_i32 s1, s0, 31
	s_lshr_b32 s1, s1, 25
	s_add_i32 s1, s0, s1
	s_ashr_i32 s4, s1, 7
	s_and_b32 s1, s1, 0xffffff80
	s_sub_i32 s1, s0, s1
	s_bfe_i32 s0, s1, 0x80000
	s_bfe_u32 s0, s0, 0x3000c
	s_add_i32 s5, s1, s0
	s_bfe_i32 s0, s5, 0x80000
	s_and_b32 s5, s5, 0xf8
	s_sub_i32 s1, s1, s5
	s_lshl_b32 s4, s4, 3
	s_sext_i32_i16 s0, s0
	s_sext_i32_i8 s1, s1
	s_lshr_b32 s0, s0, 3
	s_add_i32 s34, s4, s1
	s_ashr_i32 s35, s34, 31
	s_bfe_i64 s[8:9], s[0:1], 0x100000
	s_lshl_b64 s[4:5], s[34:35], 20
	s_lshl_b64 s[8:9], s[8:9], 20
	v_and_b32_e32 v11, 64, v0
	v_lshrrev_b32_e32 v3, 3, v0
	s_add_u32 s38, s84, s8
	v_or_b32_e32 v2, v10, v11
	v_and_or_b32 v3, v3, 48, v12
	s_addc_u32 s39, s86, s9
	s_add_i32 s35, s42, 0
	v_lshl_or_b32 v162, v3, 12, v2
	s_add_i32 m0, s35, 0x10000
	s_waitcnt vmcnt(0)
	v_lshl_or_b32 v164, v1, 12, v2
	global_load_lds_dwordx4 v162, s[38:39]
	s_add_i32 m0, s35, 0x12000
	s_add_u32 s8, s38, 0x80000
	global_load_lds_dwordx4 v164, s[38:39]
	s_addc_u32 s9, s39, 0
	s_add_i32 m0, s35, 0x14000
	v_mov_b32_e32 v163, 0
	global_load_lds_dwordx4 v162, s[8:9]
	s_add_i32 m0, s35, 0x16000
	s_add_u32 s36, s50, s4
	s_addc_u32 s37, s51, s5
	s_add_i32 s46, s35, 0x2000
	global_load_lds_dwordx4 v164, s[8:9]
	s_mov_b32 m0, s35
	s_add_u32 s4, s36, 0x80000
	global_load_lds_dwordx4 v162, s[36:37]
	s_mov_b32 m0, s46
	s_addc_u32 s5, s37, 0
	s_add_i32 s47, s35, 0x4000
	global_load_lds_dwordx4 v164, s[36:37]
	s_mov_b32 m0, s47
	s_add_i32 s54, s35, 0x6000
	global_load_lds_dwordx4 v162, s[4:5]
	s_mov_b32 m0, s54
	v_mov_b32_e32 v165, v163
	global_load_lds_dwordx4 v164, s[4:5]
	s_cmp_eq_u32 s3, 1
	s_mov_b32 s1, 0
	v_lshl_add_u64 v[8:9], s[38:39], 0, v[162:163]
	v_lshl_add_u64 v[6:7], s[38:39], 0, v[164:165]
	v_lshl_add_u64 v[2:3], s[36:37], 0, v[162:163]
	s_cselect_b64 s[4:5], -1, 0
	s_cmp_lg_u32 s3, 1
	v_lshl_add_u64 v[4:5], s[36:37], 0, v[164:165]
	s_cbranch_scc1 .LBB0_699
	s_barrier

.LBB0_708:
	s_ashr_i32 s27, s26, 31
	s_lshl_b64 s[28:29], s[26:27], 20
	s_add_u32 s28, s50, s28
	s_addc_u32 s29, s51, s29
	s_and_b64 s[30:31], s[2:3], exec
	s_cselect_b32 s27, s29, s37
	s_cselect_b32 s74, s28, s36
	s_ashr_i32 s25, s24, 31
	s_lshl_b64 s[30:31], s[24:25], 20
	s_add_u32 s30, s84, s30
	s_addc_u32 s31, s86, s31
	s_and_b64 s[40:41], s[2:3], exec
	s_cselect_b32 s25, s31, s39
	s_cselect_b32 s75, s30, s38
	s_add_u32 s36, s36, 0x80080
	s_addc_u32 s37, s37, 0
	s_add_u32 s76, s38, 0x100
	v_mov_b32_e32 v2, 0
	s_addc_u32 s77, s39, 0
	s_mov_b32 s78, -2
	v_mov_b32_e32 v3, v2
	v_mov_b32_e32 v4, v2
	v_mov_b32_e32 v5, v2
	v_mov_b32_e32 v6, v2
	v_mov_b32_e32 v7, v2
	v_mov_b32_e32 v8, v2
	v_mov_b32_e32 v9, v2
	v_mov_b32_e32 v14, v2
	v_mov_b32_e32 v15, v2
	v_mov_b32_e32 v16, v2
	v_mov_b32_e32 v17, v2
	v_mov_b32_e32 v22, v2
	v_mov_b32_e32 v23, v2
	v_mov_b32_e32 v24, v2
	v_mov_b32_e32 v25, v2
	v_mov_b32_e32 v30, v2
	v_mov_b32_e32 v31, v2
	v_mov_b32_e32 v32, v2
	v_mov_b32_e32 v33, v2
	v_mov_b32_e32 v38, v2
	v_mov_b32_e32 v39, v2
	v_mov_b32_e32 v40, v2
	v_mov_b32_e32 v41, v2
	v_mov_b32_e32 v46, v2
	v_mov_b32_e32 v47, v2
	v_mov_b32_e32 v48, v2
	v_mov_b32_e32 v49, v2
	v_mov_b32_e32 v54, v2
	v_mov_b32_e32 v55, v2
	v_mov_b32_e32 v56, v2
	v_mov_b32_e32 v57, v2
	v_mov_b32_e32 v10, v2
	v_mov_b32_e32 v11, v2
	v_mov_b32_e32 v12, v2
	v_mov_b32_e32 v13, v2
	v_mov_b32_e32 v18, v2
	v_mov_b32_e32 v19, v2
	v_mov_b32_e32 v20, v2
	v_mov_b32_e32 v21, v2
	v_mov_b32_e32 v26, v2
	v_mov_b32_e32 v27, v2
	v_mov_b32_e32 v28, v2
	v_mov_b32_e32 v29, v2
	v_mov_b32_e32 v34, v2
	v_mov_b32_e32 v35, v2
	v_mov_b32_e32 v36, v2
	v_mov_b32_e32 v37, v2
	v_mov_b32_e32 v42, v2
	v_mov_b32_e32 v43, v2
	v_mov_b32_e32 v44, v2
	v_mov_b32_e32 v45, v2
	v_mov_b32_e32 v50, v2
	v_mov_b32_e32 v51, v2
	v_mov_b32_e32 v52, v2
	v_mov_b32_e32 v53, v2
	v_mov_b32_e32 v58, v2
	v_mov_b32_e32 v59, v2
	v_mov_b32_e32 v60, v2
	v_mov_b32_e32 v61, v2
	v_mov_b32_e32 v62, v2
	v_mov_b32_e32 v63, v2
	v_mov_b32_e32 v64, v2
	v_mov_b32_e32 v65, v2
	v_mov_b32_e32 v66, v2
	v_mov_b32_e32 v67, v2
	v_mov_b32_e32 v68, v2
	v_mov_b32_e32 v69, v2
	v_mov_b32_e32 v70, v2
	v_mov_b32_e32 v71, v2
	v_mov_b32_e32 v72, v2
	v_mov_b32_e32 v73, v2
	v_mov_b32_e32 v82, v2
	v_mov_b32_e32 v83, v2
	v_mov_b32_e32 v84, v2
	v_mov_b32_e32 v85, v2
	v_mov_b32_e32 v86, v2
	v_mov_b32_e32 v87, v2
	v_mov_b32_e32 v88, v2
	v_mov_b32_e32 v89, v2
	v_mov_b32_e32 v98, v2
	v_mov_b32_e32 v99, v2
	v_mov_b32_e32 v100, v2
	v_mov_b32_e32 v101, v2
	v_mov_b32_e32 v102, v2
	v_mov_b32_e32 v103, v2
	v_mov_b32_e32 v104, v2
	v_mov_b32_e32 v105, v2
	v_mov_b32_e32 v114, v2
	v_mov_b32_e32 v115, v2
	v_mov_b32_e32 v116, v2
	v_mov_b32_e32 v117, v2
	v_mov_b32_e32 v118, v2
	v_mov_b32_e32 v119, v2
	v_mov_b32_e32 v120, v2
	v_mov_b32_e32 v121, v2
	v_mov_b32_e32 v74, v2
	v_mov_b32_e32 v75, v2
	v_mov_b32_e32 v76, v2
	v_mov_b32_e32 v77, v2
	v_mov_b32_e32 v78, v2
	v_mov_b32_e32 v79, v2
	v_mov_b32_e32 v80, v2
	v_mov_b32_e32 v81, v2
	v_mov_b32_e32 v90, v2
	v_mov_b32_e32 v91, v2
	v_mov_b32_e32 v92, v2
	v_mov_b32_e32 v93, v2
	v_mov_b32_e32 v94, v2
	v_mov_b32_e32 v95, v2
	v_mov_b32_e32 v96, v2
	v_mov_b32_e32 v97, v2
	v_mov_b32_e32 v106, v2
	v_mov_b32_e32 v107, v2
	v_mov_b32_e32 v108, v2
	v_mov_b32_e32 v109, v2
	v_mov_b32_e32 v110, v2
	v_mov_b32_e32 v111, v2
	v_mov_b32_e32 v112, v2
	v_mov_b32_e32 v113, v2
	v_mov_b32_e32 v122, v2
	v_mov_b32_e32 v123, v2
	v_mov_b32_e32 v124, v2
	v_mov_b32_e32 v125, v2
	v_mov_b32_e32 v126, v2
	v_mov_b32_e32 v127, v2
	v_mov_b32_e32 v128, v2
	v_mov_b32_e32 v129, v2
	ds_read_b128 v[130:133], v178
	ds_read_b128 v[134:137], v178 offset:1024
	ds_read_b128 v[138:141], v178 offset:2048
	ds_read_b128 v[142:145], v178 offset:3072
	ds_read_b128 v[146:149], v179
	ds_read_b128 v[150:153], v179 offset:1024
	ds_read_b128 v[154:157], v179 offset:2048
	ds_read_b128 v[158:161], v179 offset:3072
	s_add_u32 s38, s36, 0xfff80080
	s_addc_u32 s39, s37, -1
	s_cmp_eq_u32 s78, 28
	s_cselect_b32 s41, s27, s39
	s_cselect_b32 s40, s74, s38
	s_cselect_b32 s39, s25, s77
	s_cselect_b32 s38, s75, s76
	s_add_i32 m0, s35, 0xc000
	ds_read_b128 v[184:187], v180
	ds_read_b128 v[188:191], v180 offset:1024
	ds_read_b128 v[192:195], v180 offset:2048
	ds_read_b128 v[196:199], v180 offset:3072
	ds_read_b128 v[200:203], v180 offset:4096
	ds_read_b128 v[204:207], v180 offset:5120
	ds_read_b128 v[208:211], v180 offset:6144
	ds_read_b128 v[212:215], v180 offset:7168
	global_load_lds_dwordx4 v168, s[36:37]
	s_add_i32 m0, s35, 0xe000
	s_nop 0
	global_load_lds_dwordx4 v170, s[36:37]
	s_cmp_lg_u32 s32, 0
	s_cbranch_scc1 .Lpw3a
	s_waitcnt vmcnt(8)
.Lpw3a:
	s_waitcnt lgkmcnt(0)
	s_barrier
	s_setprio 1
	s_waitcnt lgkmcnt(0)
	v_mfma_i32_16x16x64_i8 v[126:129], v[130:133], v[184:187], v[126:129]
	v_mfma_i32_16x16x64_i8 v[122:125], v[138:141], v[184:187], v[122:125]
	v_mfma_i32_16x16x64_i8 v[110:113], v[130:133], v[192:195], v[110:113]
	v_mfma_i32_16x16x64_i8 v[106:109], v[138:141], v[192:195], v[106:109]
	v_mfma_i32_16x16x64_i8 v[94:97], v[130:133], v[200:203], v[94:97]
	v_mfma_i32_16x16x64_i8 v[90:93], v[138:141], v[200:203], v[90:93]
	v_mfma_i32_16x16x64_i8 v[78:81], v[130:133], v[208:211], v[78:81]
	v_mfma_i32_16x16x64_i8 v[74:77], v[138:141], v[208:211], v[74:77]
	v_mfma_i32_16x16x64_i8 v[126:129], v[134:137], v[188:191], v[126:129]
	v_mfma_i32_16x16x64_i8 v[122:125], v[142:145], v[188:191], v[122:125]
	v_mfma_i32_16x16x64_i8 v[110:113], v[134:137], v[196:199], v[110:113]
	v_mfma_i32_16x16x64_i8 v[106:109], v[142:145], v[196:199], v[106:109]
	v_mfma_i32_16x16x64_i8 v[94:97], v[134:137], v[204:207], v[94:97]
	v_mfma_i32_16x16x64_i8 v[90:93], v[142:145], v[204:207], v[90:93]
	v_mfma_i32_16x16x64_i8 v[78:81], v[134:137], v[212:215], v[78:81]
	v_mfma_i32_16x16x64_i8 v[74:77], v[142:145], v[212:215], v[74:77]
	s_setprio 0
	s_setprio 1
	v_mfma_i32_16x16x64_i8 v[118:121], v[146:149], v[184:187], v[118:121]
	v_mfma_i32_16x16x64_i8 v[114:117], v[154:157], v[184:187], v[114:117]
	v_mfma_i32_16x16x64_i8 v[102:105], v[146:149], v[192:195], v[102:105]
	v_mfma_i32_16x16x64_i8 v[98:101], v[154:157], v[192:195], v[98:101]
	v_mfma_i32_16x16x64_i8 v[86:89], v[146:149], v[200:203], v[86:89]
	v_mfma_i32_16x16x64_i8 v[82:85], v[154:157], v[200:203], v[82:85]
	v_mfma_i32_16x16x64_i8 v[70:73], v[146:149], v[208:211], v[70:73]
	v_mfma_i32_16x16x64_i8 v[66:69], v[154:157], v[208:211], v[66:69]
	v_mfma_i32_16x16x64_i8 v[118:121], v[150:153], v[188:191], v[118:121]
	v_mfma_i32_16x16x64_i8 v[114:117], v[158:161], v[188:191], v[114:117]
	v_mfma_i32_16x16x64_i8 v[102:105], v[150:153], v[196:199], v[102:105]
	v_mfma_i32_16x16x64_i8 v[98:101], v[158:161], v[196:199], v[98:101]
	v_mfma_i32_16x16x64_i8 v[86:89], v[150:153], v[204:207], v[86:89]
	v_mfma_i32_16x16x64_i8 v[82:85], v[158:161], v[204:207], v[82:85]
	v_mfma_i32_16x16x64_i8 v[70:73], v[150:153], v[212:215], v[70:73]
	v_mfma_i32_16x16x64_i8 v[66:69], v[158:161], v[212:215], v[66:69]
	s_setprio 0
	s_barrier
	s_add_i32 s79, s0, s42
	s_mov_b32 m0, s79
	ds_read_b128 v[184:187], v180 offset:16384
	ds_read_b128 v[188:191], v180 offset:17408
	ds_read_b128 v[192:195], v180 offset:18432
	ds_read_b128 v[196:199], v180 offset:19456
	ds_read_b128 v[200:203], v180 offset:20480
	ds_read_b128 v[204:207], v180 offset:21504
	ds_read_b128 v[208:211], v180 offset:22528
	ds_read_b128 v[212:215], v180 offset:23552
	global_load_lds_dwordx4 v162, s[38:39]
	s_add_i32 m0, s79, 0x2000
	s_add_u32 s82, s38, 0x80000
	s_addc_u32 s83, s39, 0
	s_add_i32 s79, s68, s42
	global_load_lds_dwordx4 v164, s[38:39]
	s_mov_b32 m0, s79
	s_nop 0
	global_load_lds_dwordx4 v162, s[82:83]
	s_add_i32 m0, s79, 0x2000
	s_nop 0
	global_load_lds_dwordx4 v164, s[82:83]
	s_mov_b32 m0, s35
	s_nop 0
	global_load_lds_dwordx4 v162, s[40:41]
	s_mov_b32 m0, s46
	s_nop 0
	global_load_lds_dwordx4 v164, s[40:41]
	s_cmp_lg_u32 s32, 0
	s_cbranch_scc1 .Lpw3b
	s_waitcnt vmcnt(8)
.Lpw3b:
	s_mov_b32 s32, 1
	s_waitcnt lgkmcnt(0)
	s_barrier
	s_setprio 1
	s_waitcnt lgkmcnt(0)
	v_mfma_i32_16x16x64_i8 v[62:65], v[130:133], v[184:187], v[62:65]
	v_mfma_i32_16x16x64_i8 v[58:61], v[138:141], v[184:187], v[58:61]
	v_mfma_i32_16x16x64_i8 v[50:53], v[130:133], v[192:195], v[50:53]
	v_mfma_i32_16x16x64_i8 v[42:45], v[138:141], v[192:195], v[42:45]
	v_mfma_i32_16x16x64_i8 v[34:37], v[130:133], v[200:203], v[34:37]
	v_mfma_i32_16x16x64_i8 v[26:29], v[138:141], v[200:203], v[26:29]
	v_mfma_i32_16x16x64_i8 v[18:21], v[130:133], v[208:211], v[18:21]
	v_mfma_i32_16x16x64_i8 v[10:13], v[138:141], v[208:211], v[10:13]
	v_mfma_i32_16x16x64_i8 v[62:65], v[134:137], v[188:191], v[62:65]
	v_mfma_i32_16x16x64_i8 v[58:61], v[142:145], v[188:191], v[58:61]
	v_mfma_i32_16x16x64_i8 v[50:53], v[134:137], v[196:199], v[50:53]
	v_mfma_i32_16x16x64_i8 v[42:45], v[142:145], v[196:199], v[42:45]
	v_mfma_i32_16x16x64_i8 v[34:37], v[134:137], v[204:207], v[34:37]
	v_mfma_i32_16x16x64_i8 v[26:29], v[142:145], v[204:207], v[26:29]
	v_mfma_i32_16x16x64_i8 v[18:21], v[134:137], v[212:215], v[18:21]
	v_mfma_i32_16x16x64_i8 v[10:13], v[142:145], v[212:215], v[10:13]
	s_setprio 0
	s_setprio 1
	v_mfma_i32_16x16x64_i8 v[54:57], v[146:149], v[184:187], v[54:57]
	v_mfma_i32_16x16x64_i8 v[46:49], v[154:157], v[184:187], v[46:49]
	v_mfma_i32_16x16x64_i8 v[38:41], v[146:149], v[192:195], v[38:41]
	v_mfma_i32_16x16x64_i8 v[30:33], v[154:157], v[192:195], v[30:33]
	v_mfma_i32_16x16x64_i8 v[22:25], v[146:149], v[200:203], v[22:25]
	v_mfma_i32_16x16x64_i8 v[14:17], v[154:157], v[200:203], v[14:17]
	v_mfma_i32_16x16x64_i8 v[6:9], v[146:149], v[208:211], v[6:9]
	v_mfma_i32_16x16x64_i8 v[2:5], v[154:157], v[208:211], v[2:5]
	v_mfma_i32_16x16x64_i8 v[54:57], v[150:153], v[188:191], v[54:57]
	v_mfma_i32_16x16x64_i8 v[46:49], v[158:161], v[188:191], v[46:49]
	v_mfma_i32_16x16x64_i8 v[38:41], v[150:153], v[196:199], v[38:41]
	v_mfma_i32_16x16x64_i8 v[30:33], v[158:161], v[196:199], v[30:33]
	v_mfma_i32_16x16x64_i8 v[22:25], v[150:153], v[204:207], v[22:25]
	v_mfma_i32_16x16x64_i8 v[14:17], v[158:161], v[204:207], v[14:17]
	v_mfma_i32_16x16x64_i8 v[6:9], v[150:153], v[212:215], v[6:9]
	v_mfma_i32_16x16x64_i8 v[2:5], v[158:161], v[212:215], v[2:5]
	s_setprio 0
	s_barrier
	s_add_i32 s79, 0, 0x18000
	s_add_i32 s80, 0, 0x1c000
	v_add_u32_e32 v142, s79, v176
	v_add_u32_e32 v158, s80, v176
	ds_read_b128 v[130:133], v142
	ds_read_b128 v[134:137], v142 offset:1024
	ds_read_b128 v[138:141], v142 offset:2048
	ds_read_b128 v[142:145], v142 offset:3072
	ds_read_b128 v[146:149], v158
	ds_read_b128 v[150:153], v158 offset:1024
	ds_read_b128 v[154:157], v158 offset:2048
	ds_read_b128 v[158:161], v158 offset:3072
	s_add_u32 s40, s40, 0x80000
	s_addc_u32 s41, s41, 0
	s_mov_b32 m0, s47
	ds_read_b128 v[184:187], v180 offset:32768
	ds_read_b128 v[188:191], v180 offset:33792
	ds_read_b128 v[192:195], v180 offset:34816
	ds_read_b128 v[196:199], v180 offset:35840
	ds_read_b128 v[200:203], v180 offset:36864
	ds_read_b128 v[204:207], v180 offset:37888
	ds_read_b128 v[208:211], v180 offset:38912
	ds_read_b128 v[212:215], v180 offset:39936
	global_load_lds_dwordx4 v162, s[40:41]
	s_mov_b32 m0, s54
	s_nop 0
	global_load_lds_dwordx4 v164, s[40:41]
	s_waitcnt vmcnt(8)
	s_waitcnt lgkmcnt(0)
	s_barrier
	s_setprio 1
	s_waitcnt lgkmcnt(0)
	v_mfma_i32_16x16x64_i8 v[126:129], v[130:133], v[184:187], v[126:129]
	v_mfma_i32_16x16x64_i8 v[122:125], v[138:141], v[184:187], v[122:125]
	v_mfma_i32_16x16x64_i8 v[110:113], v[130:133], v[192:195], v[110:113]
	v_mfma_i32_16x16x64_i8 v[106:109], v[138:141], v[192:195], v[106:109]
	v_mfma_i32_16x16x64_i8 v[94:97], v[130:133], v[200:203], v[94:97]
	v_mfma_i32_16x16x64_i8 v[90:93], v[138:141], v[200:203], v[90:93]
	v_mfma_i32_16x16x64_i8 v[78:81], v[130:133], v[208:211], v[78:81]
	v_mfma_i32_16x16x64_i8 v[74:77], v[138:141], v[208:211], v[74:77]
	v_mfma_i32_16x16x64_i8 v[126:129], v[134:137], v[188:191], v[126:129]
	v_mfma_i32_16x16x64_i8 v[122:125], v[142:145], v[188:191], v[122:125]
	v_mfma_i32_16x16x64_i8 v[110:113], v[134:137], v[196:199], v[110:113]
	v_mfma_i32_16x16x64_i8 v[106:109], v[142:145], v[196:199], v[106:109]
	v_mfma_i32_16x16x64_i8 v[94:97], v[134:137], v[204:207], v[94:97]
	v_mfma_i32_16x16x64_i8 v[90:93], v[142:145], v[204:207], v[90:93]
	v_mfma_i32_16x16x64_i8 v[78:81], v[134:137], v[212:215], v[78:81]
	v_mfma_i32_16x16x64_i8 v[74:77], v[142:145], v[212:215], v[74:77]
	s_setprio 0
	s_setprio 1
	v_mfma_i32_16x16x64_i8 v[118:121], v[146:149], v[184:187], v[118:121]
	v_mfma_i32_16x16x64_i8 v[114:117], v[154:157], v[184:187], v[114:117]
	v_mfma_i32_16x16x64_i8 v[102:105], v[146:149], v[192:195], v[102:105]
	v_mfma_i32_16x16x64_i8 v[98:101], v[154:157], v[192:195], v[98:101]
	v_mfma_i32_16x16x64_i8 v[86:89], v[146:149], v[200:203], v[86:89]
	v_mfma_i32_16x16x64_i8 v[82:85], v[154:157], v[200:203], v[82:85]
	v_mfma_i32_16x16x64_i8 v[70:73], v[146:149], v[208:211], v[70:73]
	v_mfma_i32_16x16x64_i8 v[66:69], v[154:157], v[208:211], v[66:69]
	v_mfma_i32_16x16x64_i8 v[118:121], v[150:153], v[188:191], v[118:121]
	v_mfma_i32_16x16x64_i8 v[114:117], v[158:161], v[188:191], v[114:117]
	v_mfma_i32_16x16x64_i8 v[102:105], v[150:153], v[196:199], v[102:105]
	v_mfma_i32_16x16x64_i8 v[98:101], v[158:161], v[196:199], v[98:101]
	v_mfma_i32_16x16x64_i8 v[86:89], v[150:153], v[204:207], v[86:89]
	v_mfma_i32_16x16x64_i8 v[82:85], v[158:161], v[204:207], v[82:85]
	v_mfma_i32_16x16x64_i8 v[70:73], v[150:153], v[212:215], v[70:73]
	v_mfma_i32_16x16x64_i8 v[66:69], v[158:161], v[212:215], v[66:69]
	s_setprio 0
	s_barrier
	s_add_u32 s98, s40, 0xfff80080
	s_addc_u32 s99, s41, -1
	s_add_i32 s40, s79, s42
	s_mov_b32 m0, s40
	ds_read_b128 v[184:187], v180 offset:49152
	ds_read_b128 v[188:191], v180 offset:50176
	ds_read_b128 v[192:195], v180 offset:51200
	ds_read_b128 v[196:199], v180 offset:52224
	ds_read_b128 v[200:203], v180 offset:53248
	ds_read_b128 v[204:207], v180 offset:54272
	ds_read_b128 v[208:211], v180 offset:55296
	ds_read_b128 v[212:215], v180 offset:56320
	s_add_u32 s100, s38, 0x80
	s_addc_u32 s101, s39, 0
	global_load_lds_dwordx4 v162, s[100:101]
	s_add_i32 m0, s40, 0x2000
	s_add_u32 s38, s38, 0x80080
	s_addc_u32 s39, s39, 0
	s_add_i32 s40, s80, s42
	global_load_lds_dwordx4 v164, s[100:101]
	s_mov_b32 m0, s40
	s_nop 0
	global_load_lds_dwordx4 v162, s[38:39]
	s_add_i32 m0, s40, 0x2000
	s_nop 0
	global_load_lds_dwordx4 v164, s[38:39]
	s_mov_b32 m0, s66
	s_nop 0
	global_load_lds_dwordx4 v162, s[98:99]
	s_mov_b32 m0, s67
	s_nop 0
	global_load_lds_dwordx4 v164, s[98:99]
	s_waitcnt vmcnt(8)
	s_waitcnt lgkmcnt(0)
	s_barrier
	s_setprio 1
	s_waitcnt lgkmcnt(0)
	v_mfma_i32_16x16x64_i8 v[62:65], v[130:133], v[184:187], v[62:65]
	v_mfma_i32_16x16x64_i8 v[58:61], v[138:141], v[184:187], v[58:61]
	v_mfma_i32_16x16x64_i8 v[50:53], v[130:133], v[192:195], v[50:53]
	v_mfma_i32_16x16x64_i8 v[42:45], v[138:141], v[192:195], v[42:45]
	v_mfma_i32_16x16x64_i8 v[34:37], v[130:133], v[200:203], v[34:37]
	v_mfma_i32_16x16x64_i8 v[26:29], v[138:141], v[200:203], v[26:29]
	v_mfma_i32_16x16x64_i8 v[18:21], v[130:133], v[208:211], v[18:21]
	v_mfma_i32_16x16x64_i8 v[10:13], v[138:141], v[208:211], v[10:13]
	v_mfma_i32_16x16x64_i8 v[62:65], v[134:137], v[188:191], v[62:65]
	v_mfma_i32_16x16x64_i8 v[58:61], v[142:145], v[188:191], v[58:61]
	v_mfma_i32_16x16x64_i8 v[50:53], v[134:137], v[196:199], v[50:53]
	v_mfma_i32_16x16x64_i8 v[42:45], v[142:145], v[196:199], v[42:45]
	v_mfma_i32_16x16x64_i8 v[34:37], v[134:137], v[204:207], v[34:37]
	v_mfma_i32_16x16x64_i8 v[26:29], v[142:145], v[204:207], v[26:29]
	v_mfma_i32_16x16x64_i8 v[18:21], v[134:137], v[212:215], v[18:21]
	v_mfma_i32_16x16x64_i8 v[10:13], v[142:145], v[212:215], v[10:13]
	s_setprio 0
	s_setprio 1
	v_mfma_i32_16x16x64_i8 v[54:57], v[146:149], v[184:187], v[54:57]
	v_mfma_i32_16x16x64_i8 v[46:49], v[154:157], v[184:187], v[46:49]
	v_mfma_i32_16x16x64_i8 v[38:41], v[146:149], v[192:195], v[38:41]
	v_mfma_i32_16x16x64_i8 v[30:33], v[154:157], v[192:195], v[30:33]
	v_mfma_i32_16x16x64_i8 v[22:25], v[146:149], v[200:203], v[22:25]
	v_mfma_i32_16x16x64_i8 v[14:17], v[154:157], v[200:203], v[14:17]
	v_mfma_i32_16x16x64_i8 v[6:9], v[146:149], v[208:211], v[6:9]
	v_mfma_i32_16x16x64_i8 v[2:5], v[154:157], v[208:211], v[2:5]
	v_mfma_i32_16x16x64_i8 v[54:57], v[150:153], v[188:191], v[54:57]
	v_mfma_i32_16x16x64_i8 v[46:49], v[158:161], v[188:191], v[46:49]
	v_mfma_i32_16x16x64_i8 v[38:41], v[150:153], v[196:199], v[38:41]
	v_mfma_i32_16x16x64_i8 v[30:33], v[158:161], v[196:199], v[30:33]
	v_mfma_i32_16x16x64_i8 v[22:25], v[150:153], v[204:207], v[22:25]
	v_mfma_i32_16x16x64_i8 v[14:17], v[158:161], v[204:207], v[14:17]
	v_mfma_i32_16x16x64_i8 v[6:9], v[150:153], v[212:215], v[6:9]
	v_mfma_i32_16x16x64_i8 v[2:5], v[158:161], v[212:215], v[2:5]
	s_setprio 0
	s_barrier
	s_add_i32 s78, s78, 2
	s_add_u32 s36, s36, 0x100
	s_addc_u32 s37, s37, 0
	s_add_u32 s76, s76, 0x100
	s_addc_u32 s77, s77, 0
	s_cmp_gt_u32 s78, 29

.LBB0_830:
	s_mov_b32 s32, 0
	s_cmp_lt_i32 s88, 10
	s_cselect_b64 s[0:1], -1, 0
	s_cmp_gt_i32 s89, 9
	s_cselect_b64 s[2:3], -1, 0
	s_and_b64 s[0:1], s[0:1], s[2:3]
	s_andn2_b64 vcc, exec, s[0:1]
	s_cbranch_vccnz .LBB0_923
	v_lshlrev_b32_e32 v2, 4, v0
	v_and_b32_e32 v1, 32, v0
	v_or_b32_e32 v163, 0x2000, v2
	v_bfe_u32 v162, v0, 2, 4
	v_bitop3_b32 v1, v2, v1, 48 bitop3:0x6c
	v_lshrrev_b32_e32 v2, 7, v163
	s_movk_i32 s0, 0x70
	v_and_or_b32 v169, v2, s0, v162
	v_lshlrev_b32_e32 v2, 6, v0
	v_and_b32_e32 v161, 64, v0
	v_lshrrev_b32_e32 v3, 3, v0
	s_waitcnt vmcnt(0)
	v_and_b32_e32 v164, 0x3c0, v2
	v_lshlrev_b32_e32 v2, 2, v0
	v_readfirstlane_b32 s3, v0
	v_or_b32_e32 v167, v1, v161
	v_and_or_b32 v168, v3, 48, v162
	v_and_b32_e32 v166, 15, v0
	s_cmpk_gt_i32 s33, 0xfff
	v_and_b32_e32 v165, 32, v2
	s_cbranch_scc1 .LBB0_855
	s_ashr_i32 s38, s33, 31
	s_lshr_b32 s0, s38, 29
	s_add_i32 s2, s33, s0
	s_and_b32 s0, s2, -8
	s_sub_i32 s4, s33, s0
	s_cmp_gt_i32 s4, -1
	s_cbranch_scc0 .LBB0_834
	s_lshl_b32 s5, s4, 9
	s_cbranch_execz .LBB0_835
	s_branch .LBB0_836

.LBB0_847:
	s_ashr_i32 s23, s22, 31
	s_lshl_b64 s[24:25], s[22:23], 20
	s_add_u32 s24, s20, s24
	s_addc_u32 s25, s21, s25
	s_and_b64 s[26:27], s[2:3], exec
	s_cselect_b32 s23, s25, s31
	s_cselect_b32 s66, s24, s30
	s_ashr_i32 s19, s18, 31
	s_lshl_b64 s[26:27], s[18:19], 20
	v_readlane_b32 s68, v254, 24
	s_add_u32 s26, s68, s26
	s_addc_u32 s27, s74, s27
	s_and_b64 s[36:37], s[2:3], exec
	s_cselect_b32 s19, s27, s35
	s_cselect_b32 s67, s26, s34
	s_add_u32 s30, s30, 0x80080
	s_addc_u32 s31, s31, 0
	v_readlane_b32 s69, v254, 25
	v_readlane_b32 s70, v254, 26
	s_add_u32 s68, s34, 0x100
	v_mov_b32_e32 v2, 0
	s_addc_u32 s69, s35, 0
	s_mov_b32 s70, -2
	v_mov_b32_e32 v3, v2
	v_mov_b32_e32 v4, v2
	v_mov_b32_e32 v5, v2
	v_mov_b32_e32 v6, v2
	v_mov_b32_e32 v7, v2
	v_mov_b32_e32 v8, v2
	v_mov_b32_e32 v9, v2
	v_mov_b32_e32 v18, v2
	v_mov_b32_e32 v19, v2
	v_mov_b32_e32 v20, v2
	v_mov_b32_e32 v21, v2
	v_mov_b32_e32 v22, v2
	v_mov_b32_e32 v23, v2
	v_mov_b32_e32 v24, v2
	v_mov_b32_e32 v25, v2
	v_mov_b32_e32 v34, v2
	v_mov_b32_e32 v35, v2
	v_mov_b32_e32 v36, v2
	v_mov_b32_e32 v37, v2
	v_mov_b32_e32 v38, v2
	v_mov_b32_e32 v39, v2
	v_mov_b32_e32 v40, v2
	v_mov_b32_e32 v41, v2
	v_mov_b32_e32 v50, v2
	v_mov_b32_e32 v51, v2
	v_mov_b32_e32 v52, v2
	v_mov_b32_e32 v53, v2
	v_mov_b32_e32 v54, v2
	v_mov_b32_e32 v55, v2
	v_mov_b32_e32 v56, v2
	v_mov_b32_e32 v57, v2
	v_mov_b32_e32 v10, v2
	v_mov_b32_e32 v11, v2
	v_mov_b32_e32 v12, v2
	v_mov_b32_e32 v13, v2
	v_mov_b32_e32 v14, v2
	v_mov_b32_e32 v15, v2
	v_mov_b32_e32 v16, v2
	v_mov_b32_e32 v17, v2
	v_mov_b32_e32 v26, v2
	v_mov_b32_e32 v27, v2
	v_mov_b32_e32 v28, v2
	v_mov_b32_e32 v29, v2
	v_mov_b32_e32 v30, v2
	v_mov_b32_e32 v31, v2
	v_mov_b32_e32 v32, v2
	v_mov_b32_e32 v33, v2
	v_mov_b32_e32 v42, v2
	v_mov_b32_e32 v43, v2
	v_mov_b32_e32 v44, v2
	v_mov_b32_e32 v45, v2
	v_mov_b32_e32 v46, v2
	v_mov_b32_e32 v47, v2
	v_mov_b32_e32 v48, v2
	v_mov_b32_e32 v49, v2
	v_mov_b32_e32 v58, v2
	v_mov_b32_e32 v59, v2
	v_mov_b32_e32 v60, v2
	v_mov_b32_e32 v61, v2
	v_mov_b32_e32 v62, v2
	v_mov_b32_e32 v63, v2
	v_mov_b32_e32 v64, v2
	v_mov_b32_e32 v65, v2
	v_mov_b32_e32 v66, v2
	v_mov_b32_e32 v67, v2
	v_mov_b32_e32 v68, v2
	v_mov_b32_e32 v69, v2
	v_mov_b32_e32 v70, v2
	v_mov_b32_e32 v71, v2
	v_mov_b32_e32 v72, v2
	v_mov_b32_e32 v73, v2
	v_mov_b32_e32 v82, v2
	v_mov_b32_e32 v83, v2
	v_mov_b32_e32 v84, v2
	v_mov_b32_e32 v85, v2
	v_mov_b32_e32 v86, v2
	v_mov_b32_e32 v87, v2
	v_mov_b32_e32 v88, v2
	v_mov_b32_e32 v89, v2
	v_mov_b32_e32 v98, v2
	v_mov_b32_e32 v99, v2
	v_mov_b32_e32 v100, v2
	v_mov_b32_e32 v101, v2
	v_mov_b32_e32 v102, v2
	v_mov_b32_e32 v103, v2
	v_mov_b32_e32 v104, v2
	v_mov_b32_e32 v105, v2
	v_mov_b32_e32 v130, v2
	v_mov_b32_e32 v131, v2
	v_mov_b32_e32 v132, v2
	v_mov_b32_e32 v133, v2
	v_mov_b32_e32 v134, v2
	v_mov_b32_e32 v135, v2
	v_mov_b32_e32 v136, v2
	v_mov_b32_e32 v137, v2
	v_mov_b32_e32 v74, v2
	v_mov_b32_e32 v75, v2
	v_mov_b32_e32 v76, v2
	v_mov_b32_e32 v77, v2
	v_mov_b32_e32 v78, v2
	v_mov_b32_e32 v79, v2
	v_mov_b32_e32 v80, v2
	v_mov_b32_e32 v81, v2
	v_mov_b32_e32 v90, v2
	v_mov_b32_e32 v91, v2
	v_mov_b32_e32 v92, v2
	v_mov_b32_e32 v93, v2
	v_mov_b32_e32 v94, v2
	v_mov_b32_e32 v95, v2
	v_mov_b32_e32 v96, v2
	v_mov_b32_e32 v97, v2
	v_mov_b32_e32 v114, v2
	v_mov_b32_e32 v115, v2
	v_mov_b32_e32 v116, v2
	v_mov_b32_e32 v117, v2
	v_mov_b32_e32 v118, v2
	v_mov_b32_e32 v119, v2
	v_mov_b32_e32 v120, v2
	v_mov_b32_e32 v121, v2
	v_mov_b32_e32 v138, v2
	v_mov_b32_e32 v139, v2
	v_mov_b32_e32 v140, v2
	v_mov_b32_e32 v141, v2
	v_mov_b32_e32 v142, v2
	v_mov_b32_e32 v143, v2
	v_mov_b32_e32 v144, v2
	v_mov_b32_e32 v145, v2
	v_readlane_b32 s71, v254, 27
	ds_read_b128 v[106:109], v173
	ds_read_b128 v[110:113], v173 offset:1024
	ds_read_b128 v[122:125], v173 offset:2048
	ds_read_b128 v[126:129], v173 offset:3072
	ds_read_b128 v[176:179], v174
	ds_read_b128 v[184:187], v174 offset:1024
	ds_read_b128 v[188:191], v174 offset:2048
	ds_read_b128 v[192:195], v174 offset:3072
	s_add_u32 s34, s30, 0xfff80080
	s_addc_u32 s35, s31, -1
	s_cmp_eq_u32 s70, 28
	s_cselect_b32 s37, s23, s35
	s_cselect_b32 s36, s66, s34
	s_cselect_b32 s35, s19, s69
	s_cselect_b32 s34, s67, s68
	s_add_i32 m0, s29, 0xc000
	ds_read_b128 v[196:199], v175
	ds_read_b128 v[200:203], v175 offset:1024
	ds_read_b128 v[204:207], v175 offset:2048
	ds_read_b128 v[208:211], v175 offset:3072
	ds_read_b128 v[212:215], v175 offset:4096
	ds_read_b128 v[216:219], v175 offset:5120
	ds_read_b128 v[220:223], v175 offset:6144
	ds_read_b128 v[224:227], v175 offset:7168
	global_load_lds_dwordx4 v152, s[30:31]
	s_add_i32 m0, s29, 0xe000
	s_nop 0
	global_load_lds_dwordx4 v154, s[30:31]
	s_cmp_lg_u32 s32, 0
	s_cbranch_scc1 .Lpw4a
	s_waitcnt vmcnt(8)
.Lpw4a:
	s_waitcnt lgkmcnt(0)
	s_barrier
	s_setprio 1
	s_waitcnt lgkmcnt(0)
	v_mfma_i32_16x16x64_i8 v[142:145], v[106:109], v[196:199], v[142:145]
	v_mfma_i32_16x16x64_i8 v[138:141], v[122:125], v[196:199], v[138:141]
	v_mfma_i32_16x16x64_i8 v[118:121], v[106:109], v[204:207], v[118:121]
	v_mfma_i32_16x16x64_i8 v[114:117], v[122:125], v[204:207], v[114:117]
	v_mfma_i32_16x16x64_i8 v[94:97], v[106:109], v[212:215], v[94:97]
	v_mfma_i32_16x16x64_i8 v[90:93], v[122:125], v[212:215], v[90:93]
	v_mfma_i32_16x16x64_i8 v[78:81], v[106:109], v[220:223], v[78:81]
	v_mfma_i32_16x16x64_i8 v[74:77], v[122:125], v[220:223], v[74:77]
	v_mfma_i32_16x16x64_i8 v[142:145], v[110:113], v[200:203], v[142:145]
	v_mfma_i32_16x16x64_i8 v[138:141], v[126:129], v[200:203], v[138:141]
	v_mfma_i32_16x16x64_i8 v[118:121], v[110:113], v[208:211], v[118:121]
	v_mfma_i32_16x16x64_i8 v[114:117], v[126:129], v[208:211], v[114:117]
	v_mfma_i32_16x16x64_i8 v[94:97], v[110:113], v[216:219], v[94:97]
	v_mfma_i32_16x16x64_i8 v[90:93], v[126:129], v[216:219], v[90:93]
	v_mfma_i32_16x16x64_i8 v[78:81], v[110:113], v[224:227], v[78:81]
	v_mfma_i32_16x16x64_i8 v[74:77], v[126:129], v[224:227], v[74:77]
	s_setprio 0
	s_setprio 1
	v_mfma_i32_16x16x64_i8 v[134:137], v[176:179], v[196:199], v[134:137]
	v_mfma_i32_16x16x64_i8 v[130:133], v[188:191], v[196:199], v[130:133]
	v_mfma_i32_16x16x64_i8 v[102:105], v[176:179], v[204:207], v[102:105]
	v_mfma_i32_16x16x64_i8 v[98:101], v[188:191], v[204:207], v[98:101]
	v_mfma_i32_16x16x64_i8 v[86:89], v[176:179], v[212:215], v[86:89]
	v_mfma_i32_16x16x64_i8 v[82:85], v[188:191], v[212:215], v[82:85]
	v_mfma_i32_16x16x64_i8 v[70:73], v[176:179], v[220:223], v[70:73]
	v_mfma_i32_16x16x64_i8 v[66:69], v[188:191], v[220:223], v[66:69]
	v_mfma_i32_16x16x64_i8 v[134:137], v[184:187], v[200:203], v[134:137]
	v_mfma_i32_16x16x64_i8 v[130:133], v[192:195], v[200:203], v[130:133]
	v_mfma_i32_16x16x64_i8 v[102:105], v[184:187], v[208:211], v[102:105]
	v_mfma_i32_16x16x64_i8 v[98:101], v[192:195], v[208:211], v[98:101]
	v_mfma_i32_16x16x64_i8 v[86:89], v[184:187], v[216:219], v[86:89]
	v_mfma_i32_16x16x64_i8 v[82:85], v[192:195], v[216:219], v[82:85]
	v_mfma_i32_16x16x64_i8 v[70:73], v[184:187], v[224:227], v[70:73]
	v_mfma_i32_16x16x64_i8 v[66:69], v[192:195], v[224:227], v[66:69]
	s_setprio 0
	s_barrier
	s_add_i32 s71, s51, s39
	s_mov_b32 m0, s71
	ds_read_b128 v[196:199], v175 offset:16384
	ds_read_b128 v[200:203], v175 offset:17408
	ds_read_b128 v[204:207], v175 offset:18432
	ds_read_b128 v[208:211], v175 offset:19456
	ds_read_b128 v[212:215], v175 offset:20480
	ds_read_b128 v[216:219], v175 offset:21504
	ds_read_b128 v[220:223], v175 offset:22528
	ds_read_b128 v[224:227], v175 offset:23552
	global_load_lds_dwordx4 v146, s[34:35]
	s_add_i32 m0, s71, 0x2000
	s_add_u32 s72, s34, 0x80000
	s_addc_u32 s73, s35, 0
	s_add_i32 s71, s52, s39
	global_load_lds_dwordx4 v148, s[34:35]
	s_mov_b32 m0, s71
	s_nop 0
	global_load_lds_dwordx4 v146, s[72:73]
	s_add_i32 m0, s71, 0x2000
	s_nop 0
	global_load_lds_dwordx4 v148, s[72:73]
	s_mov_b32 m0, s29
	s_nop 0
	global_load_lds_dwordx4 v146, s[36:37]
	s_mov_b32 m0, s40
	s_nop 0
	global_load_lds_dwordx4 v148, s[36:37]
	s_cmp_lg_u32 s32, 0
	s_cbranch_scc1 .Lpw4b
	s_waitcnt vmcnt(8)
.Lpw4b:
	s_mov_b32 s32, 1
	s_waitcnt lgkmcnt(0)
	s_barrier
	s_setprio 1
	s_waitcnt lgkmcnt(0)
	v_mfma_i32_16x16x64_i8 v[62:65], v[106:109], v[196:199], v[62:65]
	v_mfma_i32_16x16x64_i8 v[58:61], v[122:125], v[196:199], v[58:61]
	v_mfma_i32_16x16x64_i8 v[46:49], v[106:109], v[204:207], v[46:49]
	v_mfma_i32_16x16x64_i8 v[42:45], v[122:125], v[204:207], v[42:45]
	v_mfma_i32_16x16x64_i8 v[30:33], v[106:109], v[212:215], v[30:33]
	v_mfma_i32_16x16x64_i8 v[26:29], v[122:125], v[212:215], v[26:29]
	v_mfma_i32_16x16x64_i8 v[14:17], v[106:109], v[220:223], v[14:17]
	v_mfma_i32_16x16x64_i8 v[10:13], v[122:125], v[220:223], v[10:13]
	v_mfma_i32_16x16x64_i8 v[62:65], v[110:113], v[200:203], v[62:65]
	v_mfma_i32_16x16x64_i8 v[58:61], v[126:129], v[200:203], v[58:61]
	v_mfma_i32_16x16x64_i8 v[46:49], v[110:113], v[208:211], v[46:49]
	v_mfma_i32_16x16x64_i8 v[42:45], v[126:129], v[208:211], v[42:45]
	v_mfma_i32_16x16x64_i8 v[30:33], v[110:113], v[216:219], v[30:33]
	v_mfma_i32_16x16x64_i8 v[26:29], v[126:129], v[216:219], v[26:29]
	v_mfma_i32_16x16x64_i8 v[14:17], v[110:113], v[224:227], v[14:17]
	v_mfma_i32_16x16x64_i8 v[10:13], v[126:129], v[224:227], v[10:13]
	s_setprio 0
	s_setprio 1
	v_mfma_i32_16x16x64_i8 v[54:57], v[176:179], v[196:199], v[54:57]
	v_mfma_i32_16x16x64_i8 v[50:53], v[188:191], v[196:199], v[50:53]
	v_mfma_i32_16x16x64_i8 v[38:41], v[176:179], v[204:207], v[38:41]
	v_mfma_i32_16x16x64_i8 v[34:37], v[188:191], v[204:207], v[34:37]
	v_mfma_i32_16x16x64_i8 v[22:25], v[176:179], v[212:215], v[22:25]
	v_mfma_i32_16x16x64_i8 v[18:21], v[188:191], v[212:215], v[18:21]
	v_mfma_i32_16x16x64_i8 v[6:9], v[176:179], v[220:223], v[6:9]
	v_mfma_i32_16x16x64_i8 v[2:5], v[188:191], v[220:223], v[2:5]
	v_mfma_i32_16x16x64_i8 v[54:57], v[184:187], v[200:203], v[54:57]
	v_mfma_i32_16x16x64_i8 v[50:53], v[192:195], v[200:203], v[50:53]
	v_mfma_i32_16x16x64_i8 v[38:41], v[184:187], v[208:211], v[38:41]
	v_mfma_i32_16x16x64_i8 v[34:37], v[192:195], v[208:211], v[34:37]
	v_mfma_i32_16x16x64_i8 v[22:25], v[184:187], v[216:219], v[22:25]
	v_mfma_i32_16x16x64_i8 v[18:21], v[192:195], v[216:219], v[18:21]
	v_mfma_i32_16x16x64_i8 v[6:9], v[184:187], v[224:227], v[6:9]
	v_mfma_i32_16x16x64_i8 v[2:5], v[192:195], v[224:227], v[2:5]
	s_setprio 0
	s_barrier
	s_add_i32 s71, 0, 0x18000
	s_add_i32 s72, 0, 0x1c000
	v_add_u32_e32 v126, s71, v171
	v_add_u32_e32 v160, s72, v171
	ds_read_b128 v[106:109], v126
	ds_read_b128 v[110:113], v126 offset:1024
	ds_read_b128 v[122:125], v126 offset:2048
	ds_read_b128 v[126:129], v126 offset:3072
	ds_read_b128 v[176:179], v160
	ds_read_b128 v[184:187], v160 offset:1024
	ds_read_b128 v[188:191], v160 offset:2048
	ds_read_b128 v[192:195], v160 offset:3072
	s_add_u32 s36, s36, 0x80000
	s_addc_u32 s37, s37, 0
	s_mov_b32 m0, s41
	ds_read_b128 v[196:199], v175 offset:32768
	ds_read_b128 v[200:203], v175 offset:33792
	ds_read_b128 v[204:207], v175 offset:34816
	ds_read_b128 v[208:211], v175 offset:35840
	ds_read_b128 v[212:215], v175 offset:36864
	ds_read_b128 v[216:219], v175 offset:37888
	ds_read_b128 v[220:223], v175 offset:38912
	ds_read_b128 v[224:227], v175 offset:39936
	global_load_lds_dwordx4 v146, s[36:37]
	s_mov_b32 m0, s42
	s_nop 0
	global_load_lds_dwordx4 v148, s[36:37]
	s_waitcnt vmcnt(8)
	s_waitcnt lgkmcnt(0)
	s_barrier
	s_setprio 1
	s_waitcnt lgkmcnt(0)
	v_mfma_i32_16x16x64_i8 v[142:145], v[106:109], v[196:199], v[142:145]
	v_mfma_i32_16x16x64_i8 v[138:141], v[122:125], v[196:199], v[138:141]
	v_mfma_i32_16x16x64_i8 v[118:121], v[106:109], v[204:207], v[118:121]
	v_mfma_i32_16x16x64_i8 v[114:117], v[122:125], v[204:207], v[114:117]
	v_mfma_i32_16x16x64_i8 v[94:97], v[106:109], v[212:215], v[94:97]
	v_mfma_i32_16x16x64_i8 v[90:93], v[122:125], v[212:215], v[90:93]
	v_mfma_i32_16x16x64_i8 v[78:81], v[106:109], v[220:223], v[78:81]
	v_mfma_i32_16x16x64_i8 v[74:77], v[122:125], v[220:223], v[74:77]
	v_mfma_i32_16x16x64_i8 v[142:145], v[110:113], v[200:203], v[142:145]
	v_mfma_i32_16x16x64_i8 v[138:141], v[126:129], v[200:203], v[138:141]
	v_mfma_i32_16x16x64_i8 v[118:121], v[110:113], v[208:211], v[118:121]
	v_mfma_i32_16x16x64_i8 v[114:117], v[126:129], v[208:211], v[114:117]
	v_mfma_i32_16x16x64_i8 v[94:97], v[110:113], v[216:219], v[94:97]
	v_mfma_i32_16x16x64_i8 v[90:93], v[126:129], v[216:219], v[90:93]
	v_mfma_i32_16x16x64_i8 v[78:81], v[110:113], v[224:227], v[78:81]
	v_mfma_i32_16x16x64_i8 v[74:77], v[126:129], v[224:227], v[74:77]
	s_setprio 0
	s_setprio 1
	v_mfma_i32_16x16x64_i8 v[134:137], v[176:179], v[196:199], v[134:137]
	v_mfma_i32_16x16x64_i8 v[130:133], v[188:191], v[196:199], v[130:133]
	v_mfma_i32_16x16x64_i8 v[102:105], v[176:179], v[204:207], v[102:105]
	v_mfma_i32_16x16x64_i8 v[98:101], v[188:191], v[204:207], v[98:101]
	v_mfma_i32_16x16x64_i8 v[86:89], v[176:179], v[212:215], v[86:89]
	v_mfma_i32_16x16x64_i8 v[82:85], v[188:191], v[212:215], v[82:85]
	v_mfma_i32_16x16x64_i8 v[70:73], v[176:179], v[220:223], v[70:73]
	v_mfma_i32_16x16x64_i8 v[66:69], v[188:191], v[220:223], v[66:69]
	v_mfma_i32_16x16x64_i8 v[134:137], v[184:187], v[200:203], v[134:137]
	v_mfma_i32_16x16x64_i8 v[130:133], v[192:195], v[200:203], v[130:133]
	v_mfma_i32_16x16x64_i8 v[102:105], v[184:187], v[208:211], v[102:105]
	v_mfma_i32_16x16x64_i8 v[98:101], v[192:195], v[208:211], v[98:101]
	v_mfma_i32_16x16x64_i8 v[86:89], v[184:187], v[216:219], v[86:89]
	v_mfma_i32_16x16x64_i8 v[82:85], v[192:195], v[216:219], v[82:85]
	v_mfma_i32_16x16x64_i8 v[70:73], v[184:187], v[224:227], v[70:73]
	v_mfma_i32_16x16x64_i8 v[66:69], v[192:195], v[224:227], v[66:69]
	s_setprio 0
	s_barrier
	s_add_u32 s98, s36, 0xfff80080
	s_addc_u32 s99, s37, -1
	s_add_i32 s36, s71, s39
	s_mov_b32 m0, s36
	ds_read_b128 v[196:199], v175 offset:49152
	ds_read_b128 v[200:203], v175 offset:50176
	ds_read_b128 v[204:207], v175 offset:51200
	ds_read_b128 v[208:211], v175 offset:52224
	ds_read_b128 v[212:215], v175 offset:53248
	ds_read_b128 v[216:219], v175 offset:54272
	ds_read_b128 v[220:223], v175 offset:55296
	ds_read_b128 v[224:227], v175 offset:56320
	s_add_u32 s100, s34, 0x80
	s_addc_u32 s101, s35, 0
	global_load_lds_dwordx4 v146, s[100:101]
	s_add_i32 m0, s36, 0x2000
	s_add_u32 s34, s34, 0x80080
	s_addc_u32 s35, s35, 0
	s_add_i32 s36, s72, s39
	global_load_lds_dwordx4 v148, s[100:101]
	s_mov_b32 m0, s36
	s_nop 0
	global_load_lds_dwordx4 v146, s[34:35]
	s_add_i32 m0, s36, 0x2000
	s_nop 0
	global_load_lds_dwordx4 v148, s[34:35]
	s_mov_b32 m0, s46
	s_nop 0
	global_load_lds_dwordx4 v146, s[98:99]
	s_mov_b32 m0, s47
	s_nop 0
	global_load_lds_dwordx4 v148, s[98:99]
	s_waitcnt vmcnt(8)
	s_waitcnt lgkmcnt(0)
	s_barrier
	s_setprio 1
	s_waitcnt lgkmcnt(0)
	v_mfma_i32_16x16x64_i8 v[62:65], v[106:109], v[196:199], v[62:65]
	v_mfma_i32_16x16x64_i8 v[58:61], v[122:125], v[196:199], v[58:61]
	v_mfma_i32_16x16x64_i8 v[46:49], v[106:109], v[204:207], v[46:49]
	v_mfma_i32_16x16x64_i8 v[42:45], v[122:125], v[204:207], v[42:45]
	v_mfma_i32_16x16x64_i8 v[30:33], v[106:109], v[212:215], v[30:33]
	v_mfma_i32_16x16x64_i8 v[26:29], v[122:125], v[212:215], v[26:29]
	v_mfma_i32_16x16x64_i8 v[14:17], v[106:109], v[220:223], v[14:17]
	v_mfma_i32_16x16x64_i8 v[10:13], v[122:125], v[220:223], v[10:13]
	v_mfma_i32_16x16x64_i8 v[62:65], v[110:113], v[200:203], v[62:65]
	v_mfma_i32_16x16x64_i8 v[58:61], v[126:129], v[200:203], v[58:61]
	v_mfma_i32_16x16x64_i8 v[46:49], v[110:113], v[208:211], v[46:49]
	v_mfma_i32_16x16x64_i8 v[42:45], v[126:129], v[208:211], v[42:45]
	v_mfma_i32_16x16x64_i8 v[30:33], v[110:113], v[216:219], v[30:33]
	v_mfma_i32_16x16x64_i8 v[26:29], v[126:129], v[216:219], v[26:29]
	v_mfma_i32_16x16x64_i8 v[14:17], v[110:113], v[224:227], v[14:17]
	v_mfma_i32_16x16x64_i8 v[10:13], v[126:129], v[224:227], v[10:13]
	s_setprio 0
	s_setprio 1
	v_mfma_i32_16x16x64_i8 v[54:57], v[176:179], v[196:199], v[54:57]
	v_mfma_i32_16x16x64_i8 v[50:53], v[188:191], v[196:199], v[50:53]
	v_mfma_i32_16x16x64_i8 v[38:41], v[176:179], v[204:207], v[38:41]
	v_mfma_i32_16x16x64_i8 v[34:37], v[188:191], v[204:207], v[34:37]
	v_mfma_i32_16x16x64_i8 v[22:25], v[176:179], v[212:215], v[22:25]
	v_mfma_i32_16x16x64_i8 v[18:21], v[188:191], v[212:215], v[18:21]
	v_mfma_i32_16x16x64_i8 v[6:9], v[176:179], v[220:223], v[6:9]
	v_mfma_i32_16x16x64_i8 v[2:5], v[188:191], v[220:223], v[2:5]
	v_mfma_i32_16x16x64_i8 v[54:57], v[184:187], v[200:203], v[54:57]
	v_mfma_i32_16x16x64_i8 v[50:53], v[192:195], v[200:203], v[50:53]
	v_mfma_i32_16x16x64_i8 v[38:41], v[184:187], v[208:211], v[38:41]
	v_mfma_i32_16x16x64_i8 v[34:37], v[192:195], v[208:211], v[34:37]
	v_mfma_i32_16x16x64_i8 v[22:25], v[184:187], v[216:219], v[22:25]
	v_mfma_i32_16x16x64_i8 v[18:21], v[192:195], v[216:219], v[18:21]
	v_mfma_i32_16x16x64_i8 v[6:9], v[184:187], v[224:227], v[6:9]
	v_mfma_i32_16x16x64_i8 v[2:5], v[192:195], v[224:227], v[2:5]
	s_setprio 0
	s_barrier
	s_add_i32 s70, s70, 2
	s_add_u32 s30, s30, 0x100
	s_addc_u32 s31, s31, 0
	s_add_u32 s68, s68, 0x100
	s_addc_u32 s69, s69, 0
	s_cmp_gt_u32 s70, 29

.LBB0_923:
	s_mov_b32 s32, 0
	s_cmp_lt_i32 s88, 11
	s_cselect_b64 s[0:1], -1, 0
	s_cmp_gt_i32 s89, 10
	s_cselect_b64 s[2:3], -1, 0
	s_and_b64 s[0:1], s[0:1], s[2:3]
	s_andn2_b64 vcc, exec, s[0:1]
	s_cbranch_vccnz .LBB0_998
	s_cmpk_gt_i32 s33, 0x3ff
	v_readfirstlane_b32 s3, v0
	s_cbranch_scc1 .LBB0_944
	v_lshlrev_b32_e32 v2, 4, v0
	v_and_b32_e32 v1, 32, v0
	v_or_b32_e32 v12, 0x2000, v2
	v_bfe_u32 v11, v0, 2, 4
	v_bitop3_b32 v1, v2, v1, 48 bitop3:0x6c
	v_lshrrev_b32_e32 v2, 7, v12
	s_movk_i32 s0, 0x70
	s_ashr_i32 s37, s33, 31
	v_and_or_b32 v2, v2, s0, v11
	s_lshr_b32 s0, s37, 29
	s_add_i32 s0, s33, s0
	s_ashr_i32 s1, s0, 3
	s_and_b32 s0, s0, -8
	s_lshr_b32 s4, s3, 6
	s_sub_i32 s0, s33, s0
	s_lshr_b32 s8, s3, 8
	s_lshl_b32 s36, s4, 10
	s_lshl_b32 s5, s0, 7
	s_mul_i32 s2, s0, 0x81
	s_cmp_lt_i32 s0, 0
	s_cselect_b32 s0, s2, s5
	s_add_i32 s0, s0, s1
	s_ashr_i32 s1, s0, 31
	s_lshr_b32 s1, s1, 25
	s_add_i32 s1, s0, s1
	s_ashr_i32 s2, s1, 7
	s_and_b32 s1, s1, 0xff80
	s_sub_i32 s0, s0, s1
	s_bfe_i32 s1, s0, 0x80000
	s_bfe_u32 s1, s1, 0x3000c
	s_add_i32 s1, s0, s1
	s_lshl_b32 s5, s2, 3
	s_bfe_i32 s2, s1, 0x80000
	s_and_b32 s1, s1, 0xf8
	s_sub_i32 s0, s0, s1
	s_sext_i32_i16 s2, s2
	s_sext_i32_i8 s0, s0
	s_lshr_b32 s2, s2, 3
	s_add_i32 s26, s5, s0
	s_ashr_i32 s27, s26, 31
	s_bfe_i64 s[6:7], s[2:3], 0x100000
	s_lshl_b64 s[0:1], s[26:27], 23
	s_lshl_b64 s[6:7], s[6:7], 23
	v_and_b32_e32 v10, 64, v0
	v_lshrrev_b32_e32 v4, 3, v0
	s_add_u32 s30, s44, s6
	v_or_b32_e32 v3, v1, v10
	v_and_or_b32 v4, v4, 48, v11
	s_addc_u32 s31, s45, s7
	s_add_i32 s27, s36, 0
	v_lshl_or_b32 v144, v4, 15, v3
	s_add_i32 m0, s27, 0x10000
	v_lshl_or_b32 v146, v2, 15, v3
	global_load_lds_dwordx4 v144, s[30:31]
	s_add_i32 m0, s27, 0x12000
	s_add_u32 s6, s30, 0x400000
	global_load_lds_dwordx4 v146, s[30:31]
	s_addc_u32 s7, s31, 0
	s_add_i32 m0, s27, 0x14000
	v_mov_b32_e32 v145, 0
	global_load_lds_dwordx4 v144, s[6:7]
	s_add_i32 m0, s27, 0x16000
	s_add_u32 s28, s48, s0
	s_addc_u32 s29, s49, s1
	s_add_i32 s38, s27, 0x2000
	global_load_lds_dwordx4 v146, s[6:7]
	s_mov_b32 m0, s27
	s_add_u32 s0, s28, 0x400000
	global_load_lds_dwordx4 v144, s[28:29]
	s_mov_b32 m0, s38
	s_addc_u32 s1, s29, 0
	s_add_i32 s39, s27, 0x4000
	global_load_lds_dwordx4 v146, s[28:29]
	s_mov_b32 m0, s39
	s_add_i32 s40, s27, 0x6000
	global_load_lds_dwordx4 v144, s[0:1]
	s_mov_b32 m0, s40
	v_mov_b32_e32 v147, v145
	global_load_lds_dwordx4 v146, s[0:1]
	s_cmp_eq_u32 s8, 1
	s_mov_b32 s41, 0
	v_lshl_add_u64 v[8:9], s[30:31], 0, v[144:145]
	v_lshl_add_u64 v[6:7], s[30:31], 0, v[146:147]
	v_lshl_add_u64 v[2:3], s[28:29], 0, v[144:145]
	s_cselect_b64 s[0:1], -1, 0
	s_cmp_lg_u32 s8, 1
	v_lshl_add_u64 v[4:5], s[28:29], 0, v[146:147]
	s_cbranch_scc1 .LBB0_927
	s_barrier

.LBB0_936:
	s_ashr_i32 s21, s20, 31
	s_lshl_b64 s[22:23], s[20:21], 23
	s_add_u32 s22, s48, s22
	s_addc_u32 s23, s49, s23
	s_and_b64 s[24:25], s[2:3], exec
	s_cselect_b32 s21, s23, s29
	s_cselect_b32 s66, s22, s28
	s_ashr_i32 s19, s18, 31
	s_lshl_b64 s[24:25], s[18:19], 23
	s_add_u32 s24, s44, s24
	s_addc_u32 s25, s45, s25
	s_and_b64 s[34:35], s[2:3], exec
	s_cselect_b32 s19, s25, s31
	s_cselect_b32 s67, s24, s30
	s_add_u32 s28, s28, 0x400080
	s_addc_u32 s29, s29, 0
	s_add_u32 s68, s30, 0x100
	v_mov_b32_e32 v0, 0
	s_addc_u32 s69, s31, 0
	s_mov_b32 s70, -2
	v_mov_b32_e32 v1, v0
	v_mov_b32_e32 v2, v0
	v_mov_b32_e32 v3, v0
	v_mov_b32_e32 v4, v0
	v_mov_b32_e32 v5, v0
	v_mov_b32_e32 v6, v0
	v_mov_b32_e32 v7, v0
	v_mov_b32_e32 v8, v0
	v_mov_b32_e32 v9, v0
	v_mov_b32_e32 v10, v0
	v_mov_b32_e32 v11, v0
	v_mov_b32_e32 v16, v0
	v_mov_b32_e32 v17, v0
	v_mov_b32_e32 v18, v0
	v_mov_b32_e32 v19, v0
	v_mov_b32_e32 v24, v0
	v_mov_b32_e32 v25, v0
	v_mov_b32_e32 v26, v0
	v_mov_b32_e32 v27, v0
	v_mov_b32_e32 v32, v0
	v_mov_b32_e32 v33, v0
	v_mov_b32_e32 v34, v0
	v_mov_b32_e32 v35, v0
	v_mov_b32_e32 v40, v0
	v_mov_b32_e32 v41, v0
	v_mov_b32_e32 v42, v0
	v_mov_b32_e32 v43, v0
	s_waitcnt vmcnt(0)
	v_mov_b32_e32 v48, v0
	v_mov_b32_e32 v49, v0
	v_mov_b32_e32 v50, v0
	v_mov_b32_e32 v51, v0
	v_mov_b32_e32 v12, v0
	v_mov_b32_e32 v13, v0
	v_mov_b32_e32 v14, v0
	v_mov_b32_e32 v15, v0
	v_mov_b32_e32 v20, v0
	v_mov_b32_e32 v21, v0
	v_mov_b32_e32 v22, v0
	v_mov_b32_e32 v23, v0
	v_mov_b32_e32 v28, v0
	v_mov_b32_e32 v29, v0
	v_mov_b32_e32 v30, v0
	v_mov_b32_e32 v31, v0
	v_mov_b32_e32 v36, v0
	v_mov_b32_e32 v37, v0
	v_mov_b32_e32 v38, v0
	v_mov_b32_e32 v39, v0
	v_mov_b32_e32 v44, v0
	v_mov_b32_e32 v45, v0
	v_mov_b32_e32 v46, v0
	v_mov_b32_e32 v47, v0
	v_mov_b32_e32 v52, v0
	v_mov_b32_e32 v53, v0
	v_mov_b32_e32 v54, v0
	v_mov_b32_e32 v55, v0
	v_mov_b32_e32 v56, v0
	v_mov_b32_e32 v57, v0
	v_mov_b32_e32 v58, v0
	v_mov_b32_e32 v59, v0
	v_mov_b32_e32 v60, v0
	v_mov_b32_e32 v61, v0
	v_mov_b32_e32 v62, v0
	v_mov_b32_e32 v63, v0
	v_mov_b32_e32 v64, v0
	v_mov_b32_e32 v65, v0
	v_mov_b32_e32 v66, v0
	v_mov_b32_e32 v67, v0
	v_mov_b32_e32 v68, v0
	v_mov_b32_e32 v69, v0
	v_mov_b32_e32 v70, v0
	v_mov_b32_e32 v71, v0
	v_mov_b32_e32 v80, v0
	v_mov_b32_e32 v81, v0
	v_mov_b32_e32 v82, v0
	v_mov_b32_e32 v83, v0
	v_mov_b32_e32 v84, v0
	v_mov_b32_e32 v85, v0
	v_mov_b32_e32 v86, v0
	v_mov_b32_e32 v87, v0
	v_mov_b32_e32 v88, v0
	v_mov_b32_e32 v89, v0
	v_mov_b32_e32 v90, v0
	v_mov_b32_e32 v91, v0
	v_mov_b32_e32 v92, v0
	v_mov_b32_e32 v93, v0
	v_mov_b32_e32 v94, v0
	v_mov_b32_e32 v95, v0
	v_mov_b32_e32 v96, v0
	v_mov_b32_e32 v97, v0
	v_mov_b32_e32 v98, v0
	v_mov_b32_e32 v99, v0
	v_mov_b32_e32 v104, v0
	v_mov_b32_e32 v105, v0
	v_mov_b32_e32 v106, v0
	v_mov_b32_e32 v107, v0
	v_mov_b32_e32 v72, v0
	v_mov_b32_e32 v73, v0
	v_mov_b32_e32 v74, v0
	v_mov_b32_e32 v75, v0
	v_mov_b32_e32 v76, v0
	v_mov_b32_e32 v77, v0
	v_mov_b32_e32 v78, v0
	v_mov_b32_e32 v79, v0
	v_mov_b32_e32 v100, v0
	v_mov_b32_e32 v101, v0
	v_mov_b32_e32 v102, v0
	v_mov_b32_e32 v103, v0
	v_mov_b32_e32 v108, v0
	v_mov_b32_e32 v109, v0
	v_mov_b32_e32 v110, v0
	v_mov_b32_e32 v111, v0
	v_mov_b32_e32 v112, v0
	v_mov_b32_e32 v113, v0
	v_mov_b32_e32 v114, v0
	v_mov_b32_e32 v115, v0
	v_mov_b32_e32 v116, v0
	v_mov_b32_e32 v117, v0
	v_mov_b32_e32 v118, v0
	v_mov_b32_e32 v119, v0
	v_mov_b32_e32 v120, v0
	v_mov_b32_e32 v121, v0
	v_mov_b32_e32 v122, v0
	v_mov_b32_e32 v123, v0
	v_mov_b32_e32 v124, v0
	v_mov_b32_e32 v125, v0
	v_mov_b32_e32 v126, v0
	v_mov_b32_e32 v127, v0
	ds_read_b128 v[128:131], v159
	ds_read_b128 v[132:135], v159 offset:1024
	ds_read_b128 v[136:139], v159 offset:2048
	ds_read_b128 v[140:143], v159 offset:3072
	ds_read_b128 v[162:165], v160
	ds_read_b128 v[166:169], v160 offset:1024
	ds_read_b128 v[170:173], v160 offset:2048
	ds_read_b128 v[174:177], v160 offset:3072
	s_add_u32 s30, s28, 0xffc00080
	s_addc_u32 s31, s29, -1
	s_cmpk_eq_i32 s70, 0xfc
	s_cselect_b32 s35, s21, s31
	s_cselect_b32 s34, s66, s30
	s_cselect_b32 s31, s19, s69
	s_cselect_b32 s30, s67, s68
	s_add_i32 m0, s27, 0xc000
	ds_read_b128 v[178:181], v161
	ds_read_b128 v[184:187], v161 offset:1024
	ds_read_b128 v[188:191], v161 offset:2048
	ds_read_b128 v[192:195], v161 offset:3072
	ds_read_b128 v[196:199], v161 offset:4096
	ds_read_b128 v[200:203], v161 offset:5120
	ds_read_b128 v[204:207], v161 offset:6144
	ds_read_b128 v[208:211], v161 offset:7168
	global_load_lds_dwordx4 v148, s[28:29]
	s_add_i32 m0, s27, 0xe000
	s_nop 0
	global_load_lds_dwordx4 v150, s[28:29]
	s_cmp_lg_u32 s32, 0
	s_cbranch_scc1 .Lpw6a
	s_waitcnt vmcnt(8)
.Lpw6a:
	s_waitcnt lgkmcnt(0)
	s_barrier
	s_setprio 1
	s_waitcnt lgkmcnt(0)
	v_mfma_f32_16x16x32_bf16 v[124:127], v[128:131], v[178:181], v[124:127]
	v_mfma_f32_16x16x32_bf16 v[120:123], v[136:139], v[178:181], v[120:123]
	v_mfma_f32_16x16x32_bf16 v[116:119], v[128:131], v[188:191], v[116:119]
	v_mfma_f32_16x16x32_bf16 v[112:115], v[136:139], v[188:191], v[112:115]
	v_mfma_f32_16x16x32_bf16 v[108:111], v[128:131], v[196:199], v[108:111]
	v_mfma_f32_16x16x32_bf16 v[100:103], v[136:139], v[196:199], v[100:103]
	v_mfma_f32_16x16x32_bf16 v[76:79], v[128:131], v[204:207], v[76:79]
	v_mfma_f32_16x16x32_bf16 v[72:75], v[136:139], v[204:207], v[72:75]
	v_mfma_f32_16x16x32_bf16 v[124:127], v[132:135], v[184:187], v[124:127]
	v_mfma_f32_16x16x32_bf16 v[120:123], v[140:143], v[184:187], v[120:123]
	v_mfma_f32_16x16x32_bf16 v[116:119], v[132:135], v[192:195], v[116:119]
	v_mfma_f32_16x16x32_bf16 v[112:115], v[140:143], v[192:195], v[112:115]
	v_mfma_f32_16x16x32_bf16 v[108:111], v[132:135], v[200:203], v[108:111]
	v_mfma_f32_16x16x32_bf16 v[100:103], v[140:143], v[200:203], v[100:103]
	v_mfma_f32_16x16x32_bf16 v[76:79], v[132:135], v[208:211], v[76:79]
	v_mfma_f32_16x16x32_bf16 v[72:75], v[140:143], v[208:211], v[72:75]
	s_setprio 0
	s_setprio 1
	v_mfma_f32_16x16x32_bf16 v[104:107], v[162:165], v[178:181], v[104:107]
	v_mfma_f32_16x16x32_bf16 v[96:99], v[170:173], v[178:181], v[96:99]
	v_mfma_f32_16x16x32_bf16 v[92:95], v[162:165], v[188:191], v[92:95]
	v_mfma_f32_16x16x32_bf16 v[88:91], v[170:173], v[188:191], v[88:91]
	v_mfma_f32_16x16x32_bf16 v[84:87], v[162:165], v[196:199], v[84:87]
	v_mfma_f32_16x16x32_bf16 v[80:83], v[170:173], v[196:199], v[80:83]
	v_mfma_f32_16x16x32_bf16 v[68:71], v[162:165], v[204:207], v[68:71]
	v_mfma_f32_16x16x32_bf16 v[64:67], v[170:173], v[204:207], v[64:67]
	v_mfma_f32_16x16x32_bf16 v[104:107], v[166:169], v[184:187], v[104:107]
	v_mfma_f32_16x16x32_bf16 v[96:99], v[174:177], v[184:187], v[96:99]
	v_mfma_f32_16x16x32_bf16 v[92:95], v[166:169], v[192:195], v[92:95]
	v_mfma_f32_16x16x32_bf16 v[88:91], v[174:177], v[192:195], v[88:91]
	v_mfma_f32_16x16x32_bf16 v[84:87], v[166:169], v[200:203], v[84:87]
	v_mfma_f32_16x16x32_bf16 v[80:83], v[174:177], v[200:203], v[80:83]
	v_mfma_f32_16x16x32_bf16 v[68:71], v[166:169], v[208:211], v[68:71]
	v_mfma_f32_16x16x32_bf16 v[64:67], v[174:177], v[208:211], v[64:67]
	s_setprio 0
	s_barrier
	s_add_i32 s71, s51, s36
	s_mov_b32 m0, s71
	ds_read_b128 v[178:181], v161 offset:16384
	ds_read_b128 v[184:187], v161 offset:17408
	ds_read_b128 v[188:191], v161 offset:18432
	ds_read_b128 v[192:195], v161 offset:19456
	ds_read_b128 v[196:199], v161 offset:20480
	ds_read_b128 v[200:203], v161 offset:21504
	ds_read_b128 v[204:207], v161 offset:22528
	ds_read_b128 v[208:211], v161 offset:23552
	global_load_lds_dwordx4 v144, s[30:31]
	s_add_i32 m0, s71, 0x2000
	s_add_u32 s72, s30, 0x400000
	s_addc_u32 s73, s31, 0
	s_add_i32 s71, s52, s36
	global_load_lds_dwordx4 v146, s[30:31]
	s_mov_b32 m0, s71
	s_nop 0
	global_load_lds_dwordx4 v144, s[72:73]
	s_add_i32 m0, s71, 0x2000
	s_nop 0
	global_load_lds_dwordx4 v146, s[72:73]
	s_mov_b32 m0, s27
	s_nop 0
	global_load_lds_dwordx4 v144, s[34:35]
	s_mov_b32 m0, s38
	s_nop 0
	global_load_lds_dwordx4 v146, s[34:35]
	s_cmp_lg_u32 s32, 0
	s_cbranch_scc1 .Lpw6b
	s_waitcnt vmcnt(8)
.Lpw6b:
	s_mov_b32 s32, 1
	s_waitcnt lgkmcnt(0)
	s_barrier
	s_setprio 1
	s_waitcnt lgkmcnt(0)
	v_mfma_f32_16x16x32_bf16 v[60:63], v[128:131], v[178:181], v[60:63]
	v_mfma_f32_16x16x32_bf16 v[56:59], v[136:139], v[178:181], v[56:59]
	v_mfma_f32_16x16x32_bf16 v[52:55], v[128:131], v[188:191], v[52:55]
	v_mfma_f32_16x16x32_bf16 v[44:47], v[136:139], v[188:191], v[44:47]
	v_mfma_f32_16x16x32_bf16 v[36:39], v[128:131], v[196:199], v[36:39]
	v_mfma_f32_16x16x32_bf16 v[28:31], v[136:139], v[196:199], v[28:31]
	v_mfma_f32_16x16x32_bf16 v[20:23], v[128:131], v[204:207], v[20:23]
	v_mfma_f32_16x16x32_bf16 v[12:15], v[136:139], v[204:207], v[12:15]
	v_mfma_f32_16x16x32_bf16 v[60:63], v[132:135], v[184:187], v[60:63]
	v_mfma_f32_16x16x32_bf16 v[56:59], v[140:143], v[184:187], v[56:59]
	v_mfma_f32_16x16x32_bf16 v[52:55], v[132:135], v[192:195], v[52:55]
	v_mfma_f32_16x16x32_bf16 v[44:47], v[140:143], v[192:195], v[44:47]
	v_mfma_f32_16x16x32_bf16 v[36:39], v[132:135], v[200:203], v[36:39]
	v_mfma_f32_16x16x32_bf16 v[28:31], v[140:143], v[200:203], v[28:31]
	v_mfma_f32_16x16x32_bf16 v[20:23], v[132:135], v[208:211], v[20:23]
	v_mfma_f32_16x16x32_bf16 v[12:15], v[140:143], v[208:211], v[12:15]
	s_setprio 0
	s_setprio 1
	v_mfma_f32_16x16x32_bf16 v[48:51], v[162:165], v[178:181], v[48:51]
	v_mfma_f32_16x16x32_bf16 v[40:43], v[170:173], v[178:181], v[40:43]
	v_mfma_f32_16x16x32_bf16 v[32:35], v[162:165], v[188:191], v[32:35]
	v_mfma_f32_16x16x32_bf16 v[24:27], v[170:173], v[188:191], v[24:27]
	v_mfma_f32_16x16x32_bf16 v[16:19], v[162:165], v[196:199], v[16:19]
	v_mfma_f32_16x16x32_bf16 v[8:11], v[170:173], v[196:199], v[8:11]
	v_mfma_f32_16x16x32_bf16 v[4:7], v[162:165], v[204:207], v[4:7]
	v_mfma_f32_16x16x32_bf16 v[0:3], v[170:173], v[204:207], v[0:3]
	v_mfma_f32_16x16x32_bf16 v[48:51], v[166:169], v[184:187], v[48:51]
	v_mfma_f32_16x16x32_bf16 v[40:43], v[174:177], v[184:187], v[40:43]
	v_mfma_f32_16x16x32_bf16 v[32:35], v[166:169], v[192:195], v[32:35]
	v_mfma_f32_16x16x32_bf16 v[24:27], v[174:177], v[192:195], v[24:27]
	v_mfma_f32_16x16x32_bf16 v[16:19], v[166:169], v[200:203], v[16:19]
	v_mfma_f32_16x16x32_bf16 v[8:11], v[174:177], v[200:203], v[8:11]
	v_mfma_f32_16x16x32_bf16 v[4:7], v[166:169], v[208:211], v[4:7]
	v_mfma_f32_16x16x32_bf16 v[0:3], v[174:177], v[208:211], v[0:3]
	s_setprio 0
	s_barrier
	s_add_i32 s71, 0, 0x18000
	s_add_i32 s72, 0, 0x1c000
	v_add_u32_e32 v140, s71, v157
	v_add_u32_e32 v174, s72, v157
	ds_read_b128 v[128:131], v140
	ds_read_b128 v[132:135], v140 offset:1024
	ds_read_b128 v[136:139], v140 offset:2048
	ds_read_b128 v[140:143], v140 offset:3072
	ds_read_b128 v[162:165], v174
	ds_read_b128 v[166:169], v174 offset:1024
	ds_read_b128 v[170:173], v174 offset:2048
	ds_read_b128 v[174:177], v174 offset:3072
	s_add_u32 s34, s34, 0x400000
	s_addc_u32 s35, s35, 0
	s_mov_b32 m0, s39
	ds_read_b128 v[178:181], v161 offset:32768
	ds_read_b128 v[184:187], v161 offset:33792
	ds_read_b128 v[188:191], v161 offset:34816
	ds_read_b128 v[192:195], v161 offset:35840
	ds_read_b128 v[196:199], v161 offset:36864
	ds_read_b128 v[200:203], v161 offset:37888
	ds_read_b128 v[204:207], v161 offset:38912
	ds_read_b128 v[208:211], v161 offset:39936
	global_load_lds_dwordx4 v144, s[34:35]
	s_mov_b32 m0, s40
	s_nop 0
	global_load_lds_dwordx4 v146, s[34:35]
	s_waitcnt vmcnt(8)
	s_waitcnt lgkmcnt(0)
	s_barrier
	s_setprio 1
	s_waitcnt lgkmcnt(0)
	v_mfma_f32_16x16x32_bf16 v[124:127], v[128:131], v[178:181], v[124:127]
	v_mfma_f32_16x16x32_bf16 v[120:123], v[136:139], v[178:181], v[120:123]
	v_mfma_f32_16x16x32_bf16 v[116:119], v[128:131], v[188:191], v[116:119]
	v_mfma_f32_16x16x32_bf16 v[112:115], v[136:139], v[188:191], v[112:115]
	v_mfma_f32_16x16x32_bf16 v[108:111], v[128:131], v[196:199], v[108:111]
	v_mfma_f32_16x16x32_bf16 v[100:103], v[136:139], v[196:199], v[100:103]
	v_mfma_f32_16x16x32_bf16 v[76:79], v[128:131], v[204:207], v[76:79]
	v_mfma_f32_16x16x32_bf16 v[72:75], v[136:139], v[204:207], v[72:75]
	v_mfma_f32_16x16x32_bf16 v[124:127], v[132:135], v[184:187], v[124:127]
	v_mfma_f32_16x16x32_bf16 v[120:123], v[140:143], v[184:187], v[120:123]
	v_mfma_f32_16x16x32_bf16 v[116:119], v[132:135], v[192:195], v[116:119]
	v_mfma_f32_16x16x32_bf16 v[112:115], v[140:143], v[192:195], v[112:115]
	v_mfma_f32_16x16x32_bf16 v[108:111], v[132:135], v[200:203], v[108:111]
	v_mfma_f32_16x16x32_bf16 v[100:103], v[140:143], v[200:203], v[100:103]
	v_mfma_f32_16x16x32_bf16 v[76:79], v[132:135], v[208:211], v[76:79]
	v_mfma_f32_16x16x32_bf16 v[72:75], v[140:143], v[208:211], v[72:75]
	s_setprio 0
	s_setprio 1
	v_mfma_f32_16x16x32_bf16 v[104:107], v[162:165], v[178:181], v[104:107]
	v_mfma_f32_16x16x32_bf16 v[96:99], v[170:173], v[178:181], v[96:99]
	v_mfma_f32_16x16x32_bf16 v[92:95], v[162:165], v[188:191], v[92:95]
	v_mfma_f32_16x16x32_bf16 v[88:91], v[170:173], v[188:191], v[88:91]
	v_mfma_f32_16x16x32_bf16 v[84:87], v[162:165], v[196:199], v[84:87]
	v_mfma_f32_16x16x32_bf16 v[80:83], v[170:173], v[196:199], v[80:83]
	v_mfma_f32_16x16x32_bf16 v[68:71], v[162:165], v[204:207], v[68:71]
	v_mfma_f32_16x16x32_bf16 v[64:67], v[170:173], v[204:207], v[64:67]
	v_mfma_f32_16x16x32_bf16 v[104:107], v[166:169], v[184:187], v[104:107]
	v_mfma_f32_16x16x32_bf16 v[96:99], v[174:177], v[184:187], v[96:99]
	v_mfma_f32_16x16x32_bf16 v[92:95], v[166:169], v[192:195], v[92:95]
	v_mfma_f32_16x16x32_bf16 v[88:91], v[174:177], v[192:195], v[88:91]
	v_mfma_f32_16x16x32_bf16 v[84:87], v[166:169], v[200:203], v[84:87]
	v_mfma_f32_16x16x32_bf16 v[80:83], v[174:177], v[200:203], v[80:83]
	v_mfma_f32_16x16x32_bf16 v[68:71], v[166:169], v[208:211], v[68:71]
	v_mfma_f32_16x16x32_bf16 v[64:67], v[174:177], v[208:211], v[64:67]
	s_setprio 0
	s_barrier
	s_add_u32 s98, s34, 0xffc00080
	s_addc_u32 s99, s35, -1
	s_add_i32 s34, s71, s36
	s_mov_b32 m0, s34
	ds_read_b128 v[178:181], v161 offset:49152
	ds_read_b128 v[184:187], v161 offset:50176
	ds_read_b128 v[188:191], v161 offset:51200
	ds_read_b128 v[192:195], v161 offset:52224
	ds_read_b128 v[196:199], v161 offset:53248
	ds_read_b128 v[200:203], v161 offset:54272
	ds_read_b128 v[204:207], v161 offset:55296
	ds_read_b128 v[208:211], v161 offset:56320
	s_add_u32 s100, s30, 0x80
	s_addc_u32 s101, s31, 0
	global_load_lds_dwordx4 v144, s[100:101]
	s_add_i32 m0, s34, 0x2000
	s_add_u32 s30, s30, 0x400080
	s_addc_u32 s31, s31, 0
	s_add_i32 s34, s72, s36
	global_load_lds_dwordx4 v146, s[100:101]
	s_mov_b32 m0, s34
	s_nop 0
	global_load_lds_dwordx4 v144, s[30:31]
	s_add_i32 m0, s34, 0x2000
	s_nop 0
	global_load_lds_dwordx4 v146, s[30:31]
	s_mov_b32 m0, s47
	s_nop 0
	global_load_lds_dwordx4 v144, s[98:99]
	s_mov_b32 m0, s50
	s_nop 0
	global_load_lds_dwordx4 v146, s[98:99]
	s_waitcnt vmcnt(8)
	s_waitcnt lgkmcnt(0)
	s_barrier
	s_setprio 1
	s_waitcnt lgkmcnt(0)
	v_mfma_f32_16x16x32_bf16 v[60:63], v[128:131], v[178:181], v[60:63]
	v_mfma_f32_16x16x32_bf16 v[56:59], v[136:139], v[178:181], v[56:59]
	v_mfma_f32_16x16x32_bf16 v[52:55], v[128:131], v[188:191], v[52:55]
	v_mfma_f32_16x16x32_bf16 v[44:47], v[136:139], v[188:191], v[44:47]
	v_mfma_f32_16x16x32_bf16 v[36:39], v[128:131], v[196:199], v[36:39]
	v_mfma_f32_16x16x32_bf16 v[28:31], v[136:139], v[196:199], v[28:31]
	v_mfma_f32_16x16x32_bf16 v[20:23], v[128:131], v[204:207], v[20:23]
	v_mfma_f32_16x16x32_bf16 v[12:15], v[136:139], v[204:207], v[12:15]
	v_mfma_f32_16x16x32_bf16 v[60:63], v[132:135], v[184:187], v[60:63]
	v_mfma_f32_16x16x32_bf16 v[56:59], v[140:143], v[184:187], v[56:59]
	v_mfma_f32_16x16x32_bf16 v[52:55], v[132:135], v[192:195], v[52:55]
	v_mfma_f32_16x16x32_bf16 v[44:47], v[140:143], v[192:195], v[44:47]
	v_mfma_f32_16x16x32_bf16 v[36:39], v[132:135], v[200:203], v[36:39]
	v_mfma_f32_16x16x32_bf16 v[28:31], v[140:143], v[200:203], v[28:31]
	v_mfma_f32_16x16x32_bf16 v[20:23], v[132:135], v[208:211], v[20:23]
	v_mfma_f32_16x16x32_bf16 v[12:15], v[140:143], v[208:211], v[12:15]
	s_setprio 0
	s_setprio 1
	v_mfma_f32_16x16x32_bf16 v[48:51], v[162:165], v[178:181], v[48:51]
	v_mfma_f32_16x16x32_bf16 v[40:43], v[170:173], v[178:181], v[40:43]
	v_mfma_f32_16x16x32_bf16 v[32:35], v[162:165], v[188:191], v[32:35]
	v_mfma_f32_16x16x32_bf16 v[24:27], v[170:173], v[188:191], v[24:27]
	v_mfma_f32_16x16x32_bf16 v[16:19], v[162:165], v[196:199], v[16:19]
	v_mfma_f32_16x16x32_bf16 v[8:11], v[170:173], v[196:199], v[8:11]
	v_mfma_f32_16x16x32_bf16 v[4:7], v[162:165], v[204:207], v[4:7]
	v_mfma_f32_16x16x32_bf16 v[0:3], v[170:173], v[204:207], v[0:3]
	v_mfma_f32_16x16x32_bf16 v[48:51], v[166:169], v[184:187], v[48:51]
	v_mfma_f32_16x16x32_bf16 v[40:43], v[174:177], v[184:187], v[40:43]
	v_mfma_f32_16x16x32_bf16 v[32:35], v[166:169], v[192:195], v[32:35]
	v_mfma_f32_16x16x32_bf16 v[24:27], v[174:177], v[192:195], v[24:27]
	v_mfma_f32_16x16x32_bf16 v[16:19], v[166:169], v[200:203], v[16:19]
	v_mfma_f32_16x16x32_bf16 v[8:11], v[174:177], v[200:203], v[8:11]
	v_mfma_f32_16x16x32_bf16 v[4:7], v[166:169], v[208:211], v[4:7]
	v_mfma_f32_16x16x32_bf16 v[0:3], v[174:177], v[208:211], v[0:3]
	s_setprio 0
	s_barrier
	s_add_i32 s70, s70, 2
	s_add_u32 s28, s28, 0x100
	s_addc_u32 s29, s29, 0
	s_add_u32 s68, s68, 0x100
	s_addc_u32 s69, s69, 0
	s_cmpk_gt_u32 s70, 0xfd
